# v034 + scan consumer waves no longer raise their priority (all s_setprio removed)
# speedup vs baseline: 1.0036x; 1.0036x over previous
.LBB0_308:
	s_and_b32 s24, s27, 1
	s_mul_i32 s28, s24, 0xb000
	s_add_i32 s28, s28, 0
	v_add_u32_e32 v244, s28, v196
	v_lshl_add_u32 v246, v192, 2, s28
	v_lshl_add_u32 v176, s24, 12, v236
	s_waitcnt vmcnt(0)
	v_add_u32_e32 v247, 0xa000, v246
	ds_read2_b64 v[96:99], v247 offset1:16
	ds_read_b128 v[100:103], v244 offset:33024
	ds_read_b128 v[104:107], v244 offset:32768
	ds_read_b128 v[116:119], v244 offset:24832
	ds_read_b128 v[136:139], v244 offset:24576
	ds_read_b128 v[140:143], v244 offset:16640
	ds_read_b128 v[144:147], v244 offset:16384
	ds_read_b128 v[148:151], v244 offset:8448
	ds_read_b128 v[168:171], v244 offset:8192
	ds_read_b128 v[172:175], v244 offset:256
	ds_read_b128 v[210:213], v244
	ds_read2_b64 v[120:123], v247 offset0:32 offset1:48
	ds_read_b128 v[160:163], v244 offset:512
	ds_read_b128 v[124:127], v244 offset:768
	ds_read_b128 v[214:217], v244 offset:8704
	ds_read_b128 v[132:135], v244 offset:8960
	ds_read_b128 v[152:155], v244 offset:16896
	ds_read_b128 v[108:111], v244 offset:17152
	ds_read_b128 v[164:167], v244 offset:25088
	ds_read_b128 v[128:131], v244 offset:25344
	ds_read_b128 v[156:159], v244 offset:33280
	ds_read_b128 v[112:115], v244 offset:33536
	v_lshl_add_u32 v245, v237, 2, v176
	s_waitcnt lgkmcnt(13)
	v_pk_mul_f32 v[248:249], v[90:91], v[170:171]
	v_pk_mul_f32 v[170:171], v[94:95], v[170:171]
	v_pk_fma_f32 v[248:249], v[88:89], v[168:169], v[248:249]
	v_pk_fma_f32 v[168:169], v[92:93], v[168:169], v[170:171]
	v_add_f32_e32 v170, v248, v249
	v_add_f32_e32 v168, v168, v169
	s_waitcnt lgkmcnt(11)
	v_pk_mul_f32 v[92:93], v[92:93], v[210:211]
	v_add_f32_dpp v169, v170, v170 quad_perm:[1,0,3,2] row_mask:0xf bank_mask:0xf bound_ctrl:1
	v_add_f32_dpp v168, v168, v168 quad_perm:[1,0,3,2] row_mask:0xf bank_mask:0xf bound_ctrl:1
	v_pk_mul_f32 v[88:89], v[88:89], v[210:211]
	v_add_f32_dpp v169, v169, v169 quad_perm:[2,3,0,1] row_mask:0xf bank_mask:0xf bound_ctrl:1
	v_add_f32_dpp v168, v168, v168 quad_perm:[2,3,0,1] row_mask:0xf bank_mask:0xf bound_ctrl:1
	v_pk_mul_f32 v[90:91], v[90:91], v[212:213]
	v_add_f32_dpp v170, v169, v169 row_ror:4 row_mask:0xf bank_mask:0xf bound_ctrl:1
	v_add_f32_dpp v168, v168, v168 row_ror:4 row_mask:0xf bank_mask:0xf bound_ctrl:1
	v_pk_fma_f32 v[92:93], v[96:97], v[136:137], v[92:93] op_sel:[1,0,0]
	v_pk_mul_f32 v[94:95], v[94:95], v[212:213]
	v_pk_fma_f32 v[88:89], v[96:97], v[136:137], v[88:89] op_sel_hi:[0,1,1]
	v_add_f32_dpp v136, v170, v170 row_ror:8 row_mask:0xf bank_mask:0xf bound_ctrl:1
	v_pk_fma_f32 v[90:91], v[96:97], v[138:139], v[90:91] op_sel_hi:[0,1,1]
	v_add_f32_dpp v168, v168, v168 row_ror:8 row_mask:0xf bank_mask:0xf bound_ctrl:1
	v_pk_fma_f32 v[94:95], v[96:97], v[138:139], v[94:95] op_sel:[1,0,0]
	v_pk_fma_f32 v[90:91], v[146:147], v[136:137], v[90:91] op_sel_hi:[1,0,1] neg_lo:[1,0,0] neg_hi:[1,0,0]
	v_pk_fma_f32 v[94:95], v[146:147], v[168:169], v[94:95] op_sel_hi:[1,0,1] neg_lo:[1,0,0] neg_hi:[1,0,0]
	v_pk_fma_f32 v[88:89], v[144:145], v[136:137], v[88:89] op_sel_hi:[1,0,1] neg_lo:[1,0,0] neg_hi:[1,0,0]
	v_pk_mul_f32 v[96:97], v[106:107], v[90:91]
	v_pk_fma_f32 v[92:93], v[144:145], v[168:169], v[92:93] op_sel_hi:[1,0,1] neg_lo:[1,0,0] neg_hi:[1,0,0]
	v_pk_mul_f32 v[168:169], v[106:107], v[94:95]
	v_pk_fma_f32 v[96:97], v[104:105], v[88:89], v[96:97]
	v_pk_fma_f32 v[168:169], v[104:105], v[92:93], v[168:169]
	v_add_f32_e32 v251, v96, v97
	v_pk_mul_f32 v[96:97], v[150:151], v[90:91]
	v_pk_mul_f32 v[104:105], v[150:151], v[94:95]
	v_pk_fma_f32 v[96:97], v[148:149], v[88:89], v[96:97]
	v_pk_fma_f32 v[104:105], v[148:149], v[92:93], v[104:105]
	v_add_f32_e32 v96, v96, v97
	v_add_f32_e32 v97, v104, v105
	v_pk_mul_f32 v[88:89], v[172:173], v[88:89]
	v_add_f32_dpp v96, v96, v96 quad_perm:[1,0,3,2] row_mask:0xf bank_mask:0xf bound_ctrl:1
	v_add_f32_dpp v97, v97, v97 quad_perm:[1,0,3,2] row_mask:0xf bank_mask:0xf bound_ctrl:1
	v_pk_mul_f32 v[90:91], v[174:175], v[90:91]
	v_add_f32_dpp v96, v96, v96 quad_perm:[2,3,0,1] row_mask:0xf bank_mask:0xf bound_ctrl:1
	v_add_f32_dpp v97, v97, v97 quad_perm:[2,3,0,1] row_mask:0xf bank_mask:0xf bound_ctrl:1
	v_pk_mul_f32 v[92:93], v[172:173], v[92:93]
	v_pk_mul_f32 v[94:95], v[174:175], v[94:95]
	v_add_f32_dpp v96, v96, v96 row_ror:4 row_mask:0xf bank_mask:0xf bound_ctrl:1
	v_add_f32_dpp v97, v97, v97 row_ror:4 row_mask:0xf bank_mask:0xf bound_ctrl:1
	v_pk_fma_f32 v[88:89], v[98:99], v[116:117], v[88:89] op_sel_hi:[0,1,1]
	v_pk_fma_f32 v[90:91], v[98:99], v[118:119], v[90:91] op_sel_hi:[0,1,1]
	v_pk_fma_f32 v[92:93], v[98:99], v[116:117], v[92:93] op_sel:[1,0,0]
	v_pk_fma_f32 v[94:95], v[98:99], v[118:119], v[94:95] op_sel:[1,0,0]
	v_add_f32_dpp v96, v96, v96 row_ror:8 row_mask:0xf bank_mask:0xf bound_ctrl:1
	v_add_f32_dpp v98, v97, v97 row_ror:8 row_mask:0xf bank_mask:0xf bound_ctrl:1
	v_pk_fma_f32 v[174:175], v[142:143], v[96:97], v[90:91] op_sel_hi:[1,0,1] neg_lo:[1,0,0] neg_hi:[1,0,0]
	v_pk_fma_f32 v[172:173], v[142:143], v[98:99], v[94:95] op_sel_hi:[1,0,1] neg_lo:[1,0,0] neg_hi:[1,0,0]
	v_pk_fma_f32 v[212:213], v[140:141], v[96:97], v[88:89] op_sel_hi:[1,0,1] neg_lo:[1,0,0] neg_hi:[1,0,0]
	v_pk_fma_f32 v[210:211], v[140:141], v[98:99], v[92:93] op_sel_hi:[1,0,1] neg_lo:[1,0,0] neg_hi:[1,0,0]
	v_pk_mul_f32 v[88:89], v[102:103], v[174:175]
	v_pk_mul_f32 v[90:91], v[102:103], v[172:173]
	v_pk_fma_f32 v[88:89], v[100:101], v[212:213], v[88:89]
	v_pk_fma_f32 v[90:91], v[100:101], v[210:211], v[90:91]
	v_add_f32_e32 v250, v168, v169
	v_add_f32_e32 v252, v88, v89
	v_add_f32_e32 v253, v90, v91
	ds_read2_b64 v[96:99], v247 offset0:64 offset1:80
	ds_read_b128 v[144:147], v244 offset:1024
	ds_read_b128 v[100:103], v244 offset:1280
	ds_read_b128 v[168:171], v244 offset:9216
	ds_read_b128 v[116:119], v244 offset:9472
	ds_read_b128 v[136:139], v244 offset:17408
	ds_read_b128 v[88:91], v244 offset:17664
	ds_read_b128 v[148:151], v244 offset:25600
	ds_read_b128 v[104:107], v244 offset:25856
	ds_read_b128 v[140:143], v244 offset:33792
	ds_read_b128 v[92:95], v244 offset:34048
	s_waitcnt lgkmcnt(14)
	v_pk_mul_f32 v[248:249], v[216:217], v[174:175]
	v_pk_mul_f32 v[216:217], v[216:217], v[172:173]
	v_pk_fma_f32 v[248:249], v[214:215], v[212:213], v[248:249]
	v_pk_fma_f32 v[214:215], v[214:215], v[210:211], v[216:217]
	v_add_f32_e32 v216, v248, v249
	v_cndmask_b32_e64 v248, v251, v250, s[6:7]
	v_cndmask_b32_e64 v249, v252, v253, s[6:7]
	v_cndmask_b32_e64 v250, v250, v251, s[6:7]
	v_cndmask_b32_e64 v251, v253, v252, s[6:7]
	v_add_f32_e32 v214, v214, v215
	v_add_f32_dpp v248, v248, v250 quad_perm:[1,0,3,2] row_mask:0xf bank_mask:0xf bound_ctrl:1
	v_add_f32_dpp v249, v249, v251 quad_perm:[1,0,3,2] row_mask:0xf bank_mask:0xf bound_ctrl:1
	v_add_f32_dpp v215, v216, v216 quad_perm:[1,0,3,2] row_mask:0xf bank_mask:0xf bound_ctrl:1
	v_add_f32_dpp v214, v214, v214 quad_perm:[1,0,3,2] row_mask:0xf bank_mask:0xf bound_ctrl:1
	v_cndmask_b32_e64 v250, v248, v249, s[8:9]
	v_cndmask_b32_e64 v248, v249, v248, s[8:9]
	v_add_f32_dpp v215, v215, v215 quad_perm:[2,3,0,1] row_mask:0xf bank_mask:0xf bound_ctrl:1
	v_add_f32_dpp v216, v214, v214 quad_perm:[2,3,0,1] row_mask:0xf bank_mask:0xf bound_ctrl:1
	v_add_f32_dpp v248, v250, v248 quad_perm:[2,3,0,1] row_mask:0xf bank_mask:0xf bound_ctrl:1
	v_add_f32_dpp v214, v215, v215 row_ror:4 row_mask:0xf bank_mask:0xf bound_ctrl:1
	v_add_f32_dpp v215, v216, v216 row_ror:4 row_mask:0xf bank_mask:0xf bound_ctrl:1
	v_mov_b32_e32 v216, v177
	v_mov_b32_e32 v217, v177
	v_add_f32_dpp v248, v248, v248 row_ror:4 row_mask:0xf bank_mask:0xf bound_ctrl:1
	v_mov_b32_e32 v249, v177
	v_mov_b32_dpp v216, v214 row_ror:8 row_mask:0xf bank_mask:0xf
	v_mov_b32_dpp v217, v215 row_ror:8 row_mask:0xf bank_mask:0xf
	v_mov_b32_dpp v249, v248 row_ror:8 row_mask:0xf bank_mask:0xf
	v_add_u32_e32 v245, v245, v240
	s_and_saveexec_b64 s[78:79], s[10:11]
	v_add_f32_e32 v248, v248, v249
	ds_write_b32 v245, v248
	s_or_b64 exec, exec, s[78:79]
	v_pk_mul_f32 v[212:213], v[160:161], v[212:213]
	v_pk_mul_f32 v[174:175], v[162:163], v[174:175]
	v_pk_mul_f32 v[160:161], v[160:161], v[210:211]
	v_pk_mul_f32 v[162:163], v[162:163], v[172:173]
	v_pk_fma_f32 v[212:213], v[164:165], v[120:121], v[212:213] op_sel_hi:[1,0,1]
	v_pk_fma_f32 v[174:175], v[166:167], v[120:121], v[174:175] op_sel_hi:[1,0,1]
	v_pk_fma_f32 v[160:161], v[164:165], v[120:121], v[160:161] op_sel:[0,1,0]
	v_pk_fma_f32 v[120:121], v[166:167], v[120:121], v[162:163] op_sel:[0,1,0]
	v_add_f32_e32 v162, v214, v216
	v_add_f32_e32 v164, v215, v217
	v_pk_fma_f32 v[166:167], v[152:153], v[162:163], v[212:213] op_sel_hi:[1,0,1] neg_lo:[1,0,0] neg_hi:[1,0,0]
	v_pk_fma_f32 v[162:163], v[154:155], v[162:163], v[174:175] op_sel_hi:[1,0,1] neg_lo:[1,0,0] neg_hi:[1,0,0]
	v_pk_fma_f32 v[120:121], v[154:155], v[164:165], v[120:121] op_sel_hi:[1,0,1] neg_lo:[1,0,0] neg_hi:[1,0,0]
	s_waitcnt lgkmcnt(12)
	v_pk_mul_f32 v[154:155], v[158:159], v[162:163]
	v_pk_fma_f32 v[152:153], v[152:153], v[164:165], v[160:161] op_sel_hi:[1,0,1] neg_lo:[1,0,0] neg_hi:[1,0,0]
	v_pk_fma_f32 v[154:155], v[156:157], v[166:167], v[154:155]
	v_pk_mul_f32 v[158:159], v[158:159], v[120:121]
	v_add_f32_e32 v250, v154, v155
	v_pk_mul_f32 v[154:155], v[134:135], v[162:163]
	v_pk_mul_f32 v[134:135], v[134:135], v[120:121]
	v_pk_fma_f32 v[154:155], v[132:133], v[166:167], v[154:155]
	v_pk_fma_f32 v[132:133], v[132:133], v[152:153], v[134:135]
	v_add_f32_e32 v154, v154, v155
	v_add_f32_e32 v155, v132, v133
	v_pk_mul_f32 v[132:133], v[124:125], v[166:167]
	v_pk_mul_f32 v[134:135], v[126:127], v[162:163]
	v_pk_mul_f32 v[124:125], v[124:125], v[152:153]
	v_pk_mul_f32 v[120:121], v[126:127], v[120:121]
	v_pk_fma_f32 v[132:133], v[128:129], v[122:123], v[132:133] op_sel_hi:[1,0,1]
	v_pk_fma_f32 v[134:135], v[130:131], v[122:123], v[134:135] op_sel_hi:[1,0,1]
	v_pk_fma_f32 v[124:125], v[128:129], v[122:123], v[124:125] op_sel:[0,1,0]
	v_pk_fma_f32 v[120:121], v[130:131], v[122:123], v[120:121] op_sel:[0,1,0]
	v_add_f32_dpp v122, v154, v154 quad_perm:[1,0,3,2] row_mask:0xf bank_mask:0xf bound_ctrl:1
	v_add_f32_dpp v123, v155, v155 quad_perm:[1,0,3,2] row_mask:0xf bank_mask:0xf bound_ctrl:1
	v_pk_fma_f32 v[156:157], v[156:157], v[152:153], v[158:159]
	v_add_f32_dpp v122, v122, v122 quad_perm:[2,3,0,1] row_mask:0xf bank_mask:0xf bound_ctrl:1
	v_add_f32_dpp v123, v123, v123 quad_perm:[2,3,0,1] row_mask:0xf bank_mask:0xf bound_ctrl:1
	v_add_f32_e32 v251, v156, v157
	v_add_f32_dpp v122, v122, v122 row_ror:4 row_mask:0xf bank_mask:0xf bound_ctrl:1
	v_add_f32_dpp v123, v123, v123 row_ror:4 row_mask:0xf bank_mask:0xf bound_ctrl:1
	s_nop 0
	v_add_f32_dpp v122, v122, v122 row_ror:8 row_mask:0xf bank_mask:0xf bound_ctrl:1
	v_add_f32_dpp v126, v123, v123 row_ror:8 row_mask:0xf bank_mask:0xf bound_ctrl:1
	v_pk_fma_f32 v[212:213], v[110:111], v[122:123], v[134:135] op_sel_hi:[1,0,1] neg_lo:[1,0,0] neg_hi:[1,0,0]
	v_pk_fma_f32 v[210:211], v[110:111], v[126:127], v[120:121] op_sel_hi:[1,0,1] neg_lo:[1,0,0] neg_hi:[1,0,0]
	v_pk_fma_f32 v[216:217], v[108:109], v[122:123], v[132:133] op_sel_hi:[1,0,1] neg_lo:[1,0,0] neg_hi:[1,0,0]
	v_pk_fma_f32 v[214:215], v[108:109], v[126:127], v[124:125] op_sel_hi:[1,0,1] neg_lo:[1,0,0] neg_hi:[1,0,0]
	s_waitcnt lgkmcnt(11)
	v_pk_mul_f32 v[108:109], v[114:115], v[212:213]
	v_pk_mul_f32 v[110:111], v[114:115], v[210:211]
	v_pk_fma_f32 v[108:109], v[112:113], v[216:217], v[108:109]
	v_pk_fma_f32 v[110:111], v[112:113], v[214:215], v[110:111]
	v_add_f32_e32 v252, v108, v109
	v_add_f32_e32 v253, v110, v111
	ds_read2_b64 v[120:123], v247 offset0:96 offset1:112
	ds_read_b128 v[160:163], v244 offset:1536
	ds_read_b128 v[124:127], v244 offset:1792
	ds_read_b128 v[172:175], v244 offset:9728
	ds_read_b128 v[132:135], v244 offset:9984
	ds_read_b128 v[152:155], v244 offset:17920
	ds_read_b128 v[108:111], v244 offset:18176
	ds_read_b128 v[164:167], v244 offset:26112
	ds_read_b128 v[128:131], v244 offset:26368
	ds_read_b128 v[156:159], v244 offset:34304
	ds_read_b128 v[112:115], v244 offset:34560
	s_waitcnt lgkmcnt(14)
	v_pk_mul_f32 v[248:249], v[170:171], v[212:213]
	v_pk_mul_f32 v[170:171], v[170:171], v[210:211]
	v_pk_fma_f32 v[248:249], v[168:169], v[216:217], v[248:249]
	v_pk_fma_f32 v[168:169], v[168:169], v[214:215], v[170:171]
	v_add_f32_e32 v170, v248, v249
	v_cndmask_b32_e64 v248, v250, v251, s[6:7]
	v_cndmask_b32_e64 v249, v252, v253, s[6:7]
	v_cndmask_b32_e64 v250, v251, v250, s[6:7]
	v_cndmask_b32_e64 v251, v253, v252, s[6:7]
	v_add_f32_e32 v168, v168, v169
	v_add_f32_dpp v248, v248, v250 quad_perm:[1,0,3,2] row_mask:0xf bank_mask:0xf bound_ctrl:1
	v_add_f32_dpp v249, v249, v251 quad_perm:[1,0,3,2] row_mask:0xf bank_mask:0xf bound_ctrl:1
	v_add_f32_dpp v169, v170, v170 quad_perm:[1,0,3,2] row_mask:0xf bank_mask:0xf bound_ctrl:1
	v_add_f32_dpp v168, v168, v168 quad_perm:[1,0,3,2] row_mask:0xf bank_mask:0xf bound_ctrl:1
	v_cndmask_b32_e64 v250, v248, v249, s[8:9]
	v_cndmask_b32_e64 v248, v249, v248, s[8:9]
	v_add_f32_dpp v169, v169, v169 quad_perm:[2,3,0,1] row_mask:0xf bank_mask:0xf bound_ctrl:1
	v_add_f32_dpp v170, v168, v168 quad_perm:[2,3,0,1] row_mask:0xf bank_mask:0xf bound_ctrl:1
	v_add_f32_dpp v248, v250, v248 quad_perm:[2,3,0,1] row_mask:0xf bank_mask:0xf bound_ctrl:1
	v_add_f32_dpp v168, v169, v169 row_ror:4 row_mask:0xf bank_mask:0xf bound_ctrl:1
	v_add_f32_dpp v169, v170, v170 row_ror:4 row_mask:0xf bank_mask:0xf bound_ctrl:1
	v_mov_b32_e32 v170, 0
	v_mov_b32_e32 v171, 0
	v_add_f32_dpp v248, v248, v248 row_ror:4 row_mask:0xf bank_mask:0xf bound_ctrl:1
	v_mov_b32_e32 v249, 0
	v_mov_b32_dpp v170, v168 row_ror:8 row_mask:0xf bank_mask:0xf
	v_mov_b32_dpp v171, v169 row_ror:8 row_mask:0xf bank_mask:0xf
	v_mov_b32_dpp v249, v248 row_ror:8 row_mask:0xf bank_mask:0xf
	s_and_saveexec_b64 s[78:79], s[10:11]
	v_add_f32_e32 v248, v248, v249
	ds_write_b32 v245, v248 offset:256
	s_or_b64 exec, exec, s[78:79]
	v_pk_mul_f32 v[216:217], v[144:145], v[216:217]
	v_pk_mul_f32 v[212:213], v[146:147], v[212:213]
	v_pk_mul_f32 v[144:145], v[144:145], v[214:215]
	v_pk_mul_f32 v[146:147], v[146:147], v[210:211]
	v_pk_fma_f32 v[216:217], v[148:149], v[96:97], v[216:217] op_sel_hi:[1,0,1]
	v_pk_fma_f32 v[212:213], v[150:151], v[96:97], v[212:213] op_sel_hi:[1,0,1]
	v_pk_fma_f32 v[144:145], v[148:149], v[96:97], v[144:145] op_sel:[0,1,0]
	v_pk_fma_f32 v[96:97], v[150:151], v[96:97], v[146:147] op_sel:[0,1,0]
	v_add_f32_e32 v146, v168, v170
	v_add_f32_e32 v148, v169, v171
	v_pk_fma_f32 v[150:151], v[136:137], v[146:147], v[216:217] op_sel_hi:[1,0,1] neg_lo:[1,0,0] neg_hi:[1,0,0]
	v_pk_fma_f32 v[146:147], v[138:139], v[146:147], v[212:213] op_sel_hi:[1,0,1] neg_lo:[1,0,0] neg_hi:[1,0,0]
	v_pk_fma_f32 v[96:97], v[138:139], v[148:149], v[96:97] op_sel_hi:[1,0,1] neg_lo:[1,0,0] neg_hi:[1,0,0]
	s_waitcnt lgkmcnt(12)
	v_pk_mul_f32 v[138:139], v[142:143], v[146:147]
	v_pk_fma_f32 v[136:137], v[136:137], v[148:149], v[144:145] op_sel_hi:[1,0,1] neg_lo:[1,0,0] neg_hi:[1,0,0]
	v_pk_fma_f32 v[138:139], v[140:141], v[150:151], v[138:139]
	v_pk_mul_f32 v[142:143], v[142:143], v[96:97]
	s_nop 0
	v_pk_fma_f32 v[140:141], v[140:141], v[136:137], v[142:143]
	v_add_f32_e32 v142, v138, v139
	v_pk_mul_f32 v[138:139], v[118:119], v[146:147]
	v_pk_mul_f32 v[118:119], v[118:119], v[96:97]
	v_pk_fma_f32 v[138:139], v[116:117], v[150:151], v[138:139]
	v_pk_fma_f32 v[116:117], v[116:117], v[136:137], v[118:119]
	v_add_f32_e32 v138, v138, v139
	v_add_f32_e32 v139, v116, v117
	v_pk_mul_f32 v[96:97], v[102:103], v[96:97]
	v_pk_mul_f32 v[118:119], v[102:103], v[146:147]
	v_pk_fma_f32 v[102:103], v[106:107], v[98:99], v[96:97] op_sel:[0,1,0]
	v_add_f32_dpp v96, v138, v138 quad_perm:[1,0,3,2] row_mask:0xf bank_mask:0xf bound_ctrl:1
	v_add_f32_dpp v97, v139, v139 quad_perm:[1,0,3,2] row_mask:0xf bank_mask:0xf bound_ctrl:1
	v_pk_mul_f32 v[116:117], v[100:101], v[150:151]
	v_add_f32_dpp v96, v96, v96 quad_perm:[2,3,0,1] row_mask:0xf bank_mask:0xf bound_ctrl:1
	v_add_f32_dpp v97, v97, v97 quad_perm:[2,3,0,1] row_mask:0xf bank_mask:0xf bound_ctrl:1
	v_pk_mul_f32 v[100:101], v[100:101], v[136:137]
	v_add_f32_dpp v96, v96, v96 row_ror:4 row_mask:0xf bank_mask:0xf bound_ctrl:1
	v_add_f32_dpp v97, v97, v97 row_ror:4 row_mask:0xf bank_mask:0xf bound_ctrl:1
	v_pk_fma_f32 v[116:117], v[104:105], v[98:99], v[116:117] op_sel_hi:[1,0,1]
	v_pk_fma_f32 v[118:119], v[106:107], v[98:99], v[118:119] op_sel_hi:[1,0,1]
	v_pk_fma_f32 v[104:105], v[104:105], v[98:99], v[100:101] op_sel:[0,1,0]
	v_add_f32_dpp v96, v96, v96 row_ror:8 row_mask:0xf bank_mask:0xf bound_ctrl:1
	v_add_f32_dpp v106, v97, v97 row_ror:8 row_mask:0xf bank_mask:0xf bound_ctrl:1
	v_pk_fma_f32 v[100:101], v[88:89], v[96:97], v[116:117] op_sel_hi:[1,0,1] neg_lo:[1,0,0] neg_hi:[1,0,0]
	v_pk_fma_f32 v[96:97], v[90:91], v[96:97], v[118:119] op_sel_hi:[1,0,1] neg_lo:[1,0,0] neg_hi:[1,0,0]
	v_pk_fma_f32 v[98:99], v[88:89], v[106:107], v[104:105] op_sel_hi:[1,0,1] neg_lo:[1,0,0] neg_hi:[1,0,0]
	v_pk_fma_f32 v[88:89], v[90:91], v[106:107], v[102:103] op_sel_hi:[1,0,1] neg_lo:[1,0,0] neg_hi:[1,0,0]
	s_waitcnt lgkmcnt(11)
	v_pk_mul_f32 v[90:91], v[94:95], v[96:97]
	v_pk_mul_f32 v[94:95], v[94:95], v[88:89]
	v_pk_fma_f32 v[90:91], v[92:93], v[100:101], v[90:91]
	v_pk_fma_f32 v[92:93], v[92:93], v[98:99], v[94:95]
	v_add_f32_e32 v94, v90, v91
	v_add_f32_e32 v95, v92, v93
	v_add_f32_e32 v140, v140, v141
	s_waitcnt lgkmcnt(7)
	v_pk_mul_f32 v[90:91], v[174:175], v[96:97]
	v_pk_mul_f32 v[92:93], v[174:175], v[88:89]
	v_pk_fma_f32 v[90:91], v[172:173], v[100:101], v[90:91]
	v_pk_fma_f32 v[92:93], v[172:173], v[98:99], v[92:93]
	v_cndmask_b32_e64 v102, v142, v140, s[6:7]
	v_cndmask_b32_e64 v103, v94, v95, s[6:7]
	v_cndmask_b32_e64 v104, v140, v142, s[6:7]
	v_cndmask_b32_e64 v94, v95, v94, s[6:7]
	v_add_f32_e32 v90, v90, v91
	v_add_f32_e32 v91, v92, v93
	v_add_f32_dpp v95, v102, v104 quad_perm:[1,0,3,2] row_mask:0xf bank_mask:0xf bound_ctrl:1
	v_add_f32_dpp v94, v103, v94 quad_perm:[1,0,3,2] row_mask:0xf bank_mask:0xf bound_ctrl:1
	v_add_f32_dpp v90, v90, v90 quad_perm:[1,0,3,2] row_mask:0xf bank_mask:0xf bound_ctrl:1
	v_add_f32_dpp v91, v91, v91 quad_perm:[1,0,3,2] row_mask:0xf bank_mask:0xf bound_ctrl:1
	v_cndmask_b32_e64 v102, v95, v94, s[8:9]
	v_cndmask_b32_e64 v94, v94, v95, s[8:9]
	v_add_f32_dpp v90, v90, v90 quad_perm:[2,3,0,1] row_mask:0xf bank_mask:0xf bound_ctrl:1
	v_add_f32_dpp v91, v91, v91 quad_perm:[2,3,0,1] row_mask:0xf bank_mask:0xf bound_ctrl:1
	v_add_f32_dpp v94, v102, v94 quad_perm:[2,3,0,1] row_mask:0xf bank_mask:0xf bound_ctrl:1
	v_add_f32_dpp v90, v90, v90 row_ror:4 row_mask:0xf bank_mask:0xf bound_ctrl:1
	v_add_f32_dpp v91, v91, v91 row_ror:4 row_mask:0xf bank_mask:0xf bound_ctrl:1
	v_mov_b32_e32 v92, 0
	v_mov_b32_e32 v93, 0
	v_add_f32_dpp v94, v94, v94 row_ror:4 row_mask:0xf bank_mask:0xf bound_ctrl:1
	v_mov_b32_e32 v95, 0
	v_mov_b32_dpp v92, v90 row_ror:8 row_mask:0xf bank_mask:0xf
	v_mov_b32_dpp v93, v91 row_ror:8 row_mask:0xf bank_mask:0xf
	v_mov_b32_dpp v95, v94 row_ror:8 row_mask:0xf bank_mask:0xf
	s_and_saveexec_b64 s[78:79], s[10:11]
	v_add_f32_e32 v94, v94, v95
	ds_write_b32 v245, v94 offset:512
	s_or_b64 exec, exec, s[78:79]
	v_pk_mul_f32 v[94:95], v[160:161], v[100:101]
	v_pk_mul_f32 v[96:97], v[162:163], v[96:97]
	v_pk_mul_f32 v[88:89], v[162:163], v[88:89]
	s_waitcnt lgkmcnt(3)
	v_pk_fma_f32 v[94:95], v[164:165], v[120:121], v[94:95] op_sel_hi:[1,0,1]
	v_pk_fma_f32 v[96:97], v[166:167], v[120:121], v[96:97] op_sel_hi:[1,0,1]
	v_pk_mul_f32 v[98:99], v[160:161], v[98:99]
	v_pk_fma_f32 v[88:89], v[166:167], v[120:121], v[88:89] op_sel:[0,1,0]
	v_add_f32_e32 v90, v90, v92
	v_add_f32_e32 v92, v91, v93
	v_pk_fma_f32 v[98:99], v[164:165], v[120:121], v[98:99] op_sel:[0,1,0]
	v_pk_fma_f32 v[94:95], v[152:153], v[90:91], v[94:95] op_sel_hi:[1,0,1] neg_lo:[1,0,0] neg_hi:[1,0,0]
	v_pk_fma_f32 v[90:91], v[154:155], v[90:91], v[96:97] op_sel_hi:[1,0,1] neg_lo:[1,0,0] neg_hi:[1,0,0]
	v_pk_fma_f32 v[88:89], v[154:155], v[92:93], v[88:89] op_sel_hi:[1,0,1] neg_lo:[1,0,0] neg_hi:[1,0,0]
	v_pk_fma_f32 v[96:97], v[152:153], v[92:93], v[98:99] op_sel_hi:[1,0,1] neg_lo:[1,0,0] neg_hi:[1,0,0]
	s_waitcnt lgkmcnt(1)
	v_pk_mul_f32 v[92:93], v[158:159], v[90:91]
	v_pk_mul_f32 v[98:99], v[158:159], v[88:89]
	v_pk_fma_f32 v[92:93], v[156:157], v[94:95], v[92:93]
	v_pk_fma_f32 v[98:99], v[156:157], v[96:97], v[98:99]
	v_add_f32_e32 v101, v92, v93
	v_add_f32_e32 v102, v98, v99
	v_pk_mul_f32 v[92:93], v[134:135], v[90:91]
	v_pk_mul_f32 v[98:99], v[134:135], v[88:89]
	v_pk_fma_f32 v[92:93], v[132:133], v[94:95], v[92:93]
	v_pk_fma_f32 v[98:99], v[132:133], v[96:97], v[98:99]
	v_add_f32_e32 v100, v92, v93
	v_add_f32_e32 v98, v98, v99
	v_pk_mul_f32 v[88:89], v[126:127], v[88:89]
	v_pk_mul_f32 v[92:93], v[124:125], v[94:95]
	v_pk_mul_f32 v[94:95], v[124:125], v[96:97]
	v_pk_fma_f32 v[96:97], v[130:131], v[122:123], v[88:89] op_sel:[0,1,0]
	v_add_f32_dpp v88, v100, v100 quad_perm:[1,0,3,2] row_mask:0xf bank_mask:0xf bound_ctrl:1
	v_add_f32_dpp v89, v98, v98 quad_perm:[1,0,3,2] row_mask:0xf bank_mask:0xf bound_ctrl:1
	v_pk_mul_f32 v[90:91], v[126:127], v[90:91]
	v_add_f32_dpp v88, v88, v88 quad_perm:[2,3,0,1] row_mask:0xf bank_mask:0xf bound_ctrl:1
	v_add_f32_dpp v89, v89, v89 quad_perm:[2,3,0,1] row_mask:0xf bank_mask:0xf bound_ctrl:1
	v_pk_fma_f32 v[92:93], v[128:129], v[122:123], v[92:93] op_sel_hi:[1,0,1]
	v_add_f32_dpp v88, v88, v88 row_ror:4 row_mask:0xf bank_mask:0xf bound_ctrl:1
	v_add_f32_dpp v89, v89, v89 row_ror:4 row_mask:0xf bank_mask:0xf bound_ctrl:1
	v_pk_fma_f32 v[90:91], v[130:131], v[122:123], v[90:91] op_sel_hi:[1,0,1]
	v_pk_fma_f32 v[94:95], v[128:129], v[122:123], v[94:95] op_sel:[0,1,0]
	v_add_f32_dpp v98, v88, v88 row_ror:8 row_mask:0xf bank_mask:0xf bound_ctrl:1
	v_add_f32_dpp v100, v89, v89 row_ror:8 row_mask:0xf bank_mask:0xf bound_ctrl:1
	v_pk_fma_f32 v[88:89], v[108:109], v[98:99], v[92:93] op_sel_hi:[1,0,1] neg_lo:[1,0,0] neg_hi:[1,0,0]
	v_pk_fma_f32 v[90:91], v[110:111], v[98:99], v[90:91] op_sel_hi:[1,0,1] neg_lo:[1,0,0] neg_hi:[1,0,0]
	v_pk_fma_f32 v[92:93], v[108:109], v[100:101], v[94:95] op_sel_hi:[1,0,1] neg_lo:[1,0,0] neg_hi:[1,0,0]
	v_pk_fma_f32 v[94:95], v[110:111], v[100:101], v[96:97] op_sel_hi:[1,0,1] neg_lo:[1,0,0] neg_hi:[1,0,0]
	s_waitcnt lgkmcnt(0)
	v_pk_mul_f32 v[96:97], v[114:115], v[90:91]
	v_pk_mul_f32 v[98:99], v[114:115], v[94:95]
	v_pk_fma_f32 v[96:97], v[112:113], v[88:89], v[96:97]
	v_pk_fma_f32 v[98:99], v[112:113], v[92:93], v[98:99]
	v_add_f32_e32 v96, v96, v97
	v_add_f32_e32 v97, v98, v99
	v_cndmask_b32_e64 v98, v101, v102, s[6:7]
	v_cndmask_b32_e64 v99, v96, v97, s[6:7]
	v_cndmask_b32_e64 v100, v102, v101, s[6:7]
	v_cndmask_b32_e64 v96, v97, v96, s[6:7]
	s_nop 0
	v_add_f32_dpp v97, v98, v100 quad_perm:[1,0,3,2] row_mask:0xf bank_mask:0xf bound_ctrl:1
	v_add_f32_dpp v96, v99, v96 quad_perm:[1,0,3,2] row_mask:0xf bank_mask:0xf bound_ctrl:1
	v_cndmask_b32_e64 v98, v97, v96, s[8:9]
	v_cndmask_b32_e64 v96, v96, v97, s[8:9]
	v_mov_b32_e32 v97, 0
	s_nop 0
	v_add_f32_dpp v96, v98, v96 quad_perm:[2,3,0,1] row_mask:0xf bank_mask:0xf bound_ctrl:1
	s_nop 1
	v_add_f32_dpp v96, v96, v96 row_ror:4 row_mask:0xf bank_mask:0xf bound_ctrl:1
	s_nop 1
	v_mov_b32_dpp v97, v96 row_ror:8 row_mask:0xf bank_mask:0xf
	s_and_saveexec_b64 s[78:79], s[10:11]
	v_add3_u32 v98, v176, v239, v197
	v_add_f32_e32 v96, v96, v97
	ds_write_b32 v98, v96 offset:768
	s_or_b64 exec, exec, s[78:79]
	s_add_i32 s24, s70, 0xffffff00
	s_lshr_b32 s24, s24, 5
	s_lshl_b64 s[28:29], s[24:25], 10
	s_lshl_b32 s24, s70, 5
	s_and_b32 s24, s24, 0x3e0
	s_or_b32 s24, s28, s24
	v_mov_b32_e32 v97, s29
	v_or_b32_e32 v96, s24, v192
	v_lshlrev_b64 v[96:97], 8, v[96:97]
	s_add_i32 s24, s70, s94
	v_lshl_add_u64 v[96:97], v[198:199], 0, v[96:97]
	s_cmpk_gt_i32 s24, 0x10ff
	global_store_dwordx4 v[96:97], v[88:91], off
	global_store_dwordx4 v[96:97], v[92:95], off offset:256
	s_cbranch_scc1 .LBB0_327
	ds_read2_b64 v[88:91], v247 offset0:128 offset1:144
	ds_read_b128 v[92:95], v244 offset:35072
	ds_read_b128 v[96:99], v244 offset:34816
	ds_read_b128 v[108:111], v244 offset:26880
	ds_read_b128 v[128:131], v244 offset:26624
	ds_read_b128 v[132:135], v244 offset:18688
	ds_read_b128 v[136:139], v244 offset:18432
	ds_read_b128 v[140:143], v244 offset:10496
	ds_read_b128 v[160:163], v244 offset:10240
	ds_read_b128 v[164:167], v244 offset:2304
	ds_read_b128 v[168:171], v244 offset:2048
	ds_read2_b64 v[112:115], v247 offset0:160 offset1:176
	ds_read_b128 v[152:155], v244 offset:2560
	ds_read_b128 v[116:119], v244 offset:2816
	ds_read_b128 v[172:175], v244 offset:10752
	ds_read_b128 v[124:127], v244 offset:11008
	ds_read_b128 v[144:147], v244 offset:18944
	ds_read_b128 v[100:103], v244 offset:19200
	ds_read_b128 v[156:159], v244 offset:27136
	ds_read_b128 v[120:123], v244 offset:27392
	ds_read_b128 v[148:151], v244 offset:35328
	ds_read_b128 v[104:107], v244 offset:35584
	s_waitcnt lgkmcnt(13)
	v_pk_mul_f32 v[210:211], v[82:83], v[162:163]
	v_pk_mul_f32 v[162:163], v[86:87], v[162:163]
	v_pk_fma_f32 v[210:211], v[80:81], v[160:161], v[210:211]
	v_pk_fma_f32 v[160:161], v[84:85], v[160:161], v[162:163]
	v_add_f32_e32 v162, v210, v211
	v_add_f32_e32 v160, v160, v161
	s_waitcnt lgkmcnt(11)
	v_pk_mul_f32 v[84:85], v[84:85], v[168:169]
	v_add_f32_dpp v161, v162, v162 quad_perm:[1,0,3,2] row_mask:0xf bank_mask:0xf bound_ctrl:1
	v_add_f32_dpp v160, v160, v160 quad_perm:[1,0,3,2] row_mask:0xf bank_mask:0xf bound_ctrl:1
	v_pk_mul_f32 v[80:81], v[80:81], v[168:169]
	v_add_f32_dpp v161, v161, v161 quad_perm:[2,3,0,1] row_mask:0xf bank_mask:0xf bound_ctrl:1
	v_add_f32_dpp v160, v160, v160 quad_perm:[2,3,0,1] row_mask:0xf bank_mask:0xf bound_ctrl:1
	v_pk_mul_f32 v[82:83], v[82:83], v[170:171]
	v_add_f32_dpp v162, v161, v161 row_ror:4 row_mask:0xf bank_mask:0xf bound_ctrl:1
	v_add_f32_dpp v160, v160, v160 row_ror:4 row_mask:0xf bank_mask:0xf bound_ctrl:1
	v_pk_fma_f32 v[84:85], v[88:89], v[128:129], v[84:85] op_sel:[1,0,0]
	v_pk_mul_f32 v[86:87], v[86:87], v[170:171]
	v_pk_fma_f32 v[80:81], v[88:89], v[128:129], v[80:81] op_sel_hi:[0,1,1]
	v_add_f32_dpp v128, v162, v162 row_ror:8 row_mask:0xf bank_mask:0xf bound_ctrl:1
	v_pk_fma_f32 v[82:83], v[88:89], v[130:131], v[82:83] op_sel_hi:[0,1,1]
	v_add_f32_dpp v160, v160, v160 row_ror:8 row_mask:0xf bank_mask:0xf bound_ctrl:1
	v_pk_fma_f32 v[86:87], v[88:89], v[130:131], v[86:87] op_sel:[1,0,0]
	v_pk_fma_f32 v[82:83], v[138:139], v[128:129], v[82:83] op_sel_hi:[1,0,1] neg_lo:[1,0,0] neg_hi:[1,0,0]
	v_pk_fma_f32 v[86:87], v[138:139], v[160:161], v[86:87] op_sel_hi:[1,0,1] neg_lo:[1,0,0] neg_hi:[1,0,0]
	v_pk_fma_f32 v[80:81], v[136:137], v[128:129], v[80:81] op_sel_hi:[1,0,1] neg_lo:[1,0,0] neg_hi:[1,0,0]
	v_pk_mul_f32 v[88:89], v[98:99], v[82:83]
	v_pk_fma_f32 v[84:85], v[136:137], v[160:161], v[84:85] op_sel_hi:[1,0,1] neg_lo:[1,0,0] neg_hi:[1,0,0]
	v_pk_mul_f32 v[160:161], v[98:99], v[86:87]
	v_pk_fma_f32 v[88:89], v[96:97], v[80:81], v[88:89]
	v_pk_fma_f32 v[160:161], v[96:97], v[84:85], v[160:161]
	v_add_f32_e32 v213, v88, v89
	v_pk_mul_f32 v[88:89], v[142:143], v[82:83]
	v_pk_mul_f32 v[96:97], v[142:143], v[86:87]
	v_pk_fma_f32 v[88:89], v[140:141], v[80:81], v[88:89]
	v_pk_fma_f32 v[96:97], v[140:141], v[84:85], v[96:97]
	v_add_f32_e32 v88, v88, v89
	v_add_f32_e32 v89, v96, v97
	v_pk_mul_f32 v[80:81], v[164:165], v[80:81]
	v_add_f32_dpp v88, v88, v88 quad_perm:[1,0,3,2] row_mask:0xf bank_mask:0xf bound_ctrl:1
	v_add_f32_dpp v89, v89, v89 quad_perm:[1,0,3,2] row_mask:0xf bank_mask:0xf bound_ctrl:1
	v_pk_mul_f32 v[82:83], v[166:167], v[82:83]
	v_add_f32_dpp v88, v88, v88 quad_perm:[2,3,0,1] row_mask:0xf bank_mask:0xf bound_ctrl:1
	v_add_f32_dpp v89, v89, v89 quad_perm:[2,3,0,1] row_mask:0xf bank_mask:0xf bound_ctrl:1
	v_pk_mul_f32 v[84:85], v[164:165], v[84:85]
	v_pk_mul_f32 v[86:87], v[166:167], v[86:87]
	v_add_f32_dpp v88, v88, v88 row_ror:4 row_mask:0xf bank_mask:0xf bound_ctrl:1
	v_add_f32_dpp v89, v89, v89 row_ror:4 row_mask:0xf bank_mask:0xf bound_ctrl:1
	v_pk_fma_f32 v[80:81], v[90:91], v[108:109], v[80:81] op_sel_hi:[0,1,1]
	v_pk_fma_f32 v[82:83], v[90:91], v[110:111], v[82:83] op_sel_hi:[0,1,1]
	v_pk_fma_f32 v[84:85], v[90:91], v[108:109], v[84:85] op_sel:[1,0,0]
	v_pk_fma_f32 v[86:87], v[90:91], v[110:111], v[86:87] op_sel:[1,0,0]
	v_add_f32_dpp v88, v88, v88 row_ror:8 row_mask:0xf bank_mask:0xf bound_ctrl:1
	v_add_f32_dpp v90, v89, v89 row_ror:8 row_mask:0xf bank_mask:0xf bound_ctrl:1
	v_pk_fma_f32 v[166:167], v[134:135], v[88:89], v[82:83] op_sel_hi:[1,0,1] neg_lo:[1,0,0] neg_hi:[1,0,0]
	v_pk_fma_f32 v[164:165], v[134:135], v[90:91], v[86:87] op_sel_hi:[1,0,1] neg_lo:[1,0,0] neg_hi:[1,0,0]
	v_pk_fma_f32 v[170:171], v[132:133], v[88:89], v[80:81] op_sel_hi:[1,0,1] neg_lo:[1,0,0] neg_hi:[1,0,0]
	v_pk_fma_f32 v[168:169], v[132:133], v[90:91], v[84:85] op_sel_hi:[1,0,1] neg_lo:[1,0,0] neg_hi:[1,0,0]
	v_pk_mul_f32 v[80:81], v[94:95], v[166:167]
	v_pk_mul_f32 v[82:83], v[94:95], v[164:165]
	v_pk_fma_f32 v[80:81], v[92:93], v[170:171], v[80:81]
	v_pk_fma_f32 v[82:83], v[92:93], v[168:169], v[82:83]
	v_add_f32_e32 v212, v160, v161
	v_add_f32_e32 v214, v80, v81
	v_add_f32_e32 v215, v82, v83
	ds_read2_b64 v[88:91], v247 offset0:192 offset1:208
	ds_read_b128 v[136:139], v244 offset:3072
	ds_read_b128 v[92:95], v244 offset:3328
	ds_read_b128 v[160:163], v244 offset:11264
	ds_read_b128 v[108:111], v244 offset:11520
	ds_read_b128 v[128:131], v244 offset:19456
	ds_read_b128 v[80:83], v244 offset:19712
	ds_read_b128 v[140:143], v244 offset:27648
	ds_read_b128 v[96:99], v244 offset:27904
	ds_read_b128 v[132:135], v244 offset:35840
	ds_read_b128 v[84:87], v244 offset:36096
	s_waitcnt lgkmcnt(14)
	v_pk_mul_f32 v[210:211], v[174:175], v[166:167]
	v_pk_mul_f32 v[174:175], v[174:175], v[164:165]
	v_pk_fma_f32 v[210:211], v[172:173], v[170:171], v[210:211]
	v_pk_fma_f32 v[172:173], v[172:173], v[168:169], v[174:175]
	v_add_f32_e32 v174, v210, v211
	v_cndmask_b32_e64 v210, v213, v212, s[6:7]
	v_cndmask_b32_e64 v211, v214, v215, s[6:7]
	v_cndmask_b32_e64 v212, v212, v213, s[6:7]
	v_cndmask_b32_e64 v213, v215, v214, s[6:7]
	v_add_f32_e32 v172, v172, v173
	v_add_f32_dpp v210, v210, v212 quad_perm:[1,0,3,2] row_mask:0xf bank_mask:0xf bound_ctrl:1
	v_add_f32_dpp v211, v211, v213 quad_perm:[1,0,3,2] row_mask:0xf bank_mask:0xf bound_ctrl:1
	v_add_f32_dpp v173, v174, v174 quad_perm:[1,0,3,2] row_mask:0xf bank_mask:0xf bound_ctrl:1
	v_add_f32_dpp v172, v172, v172 quad_perm:[1,0,3,2] row_mask:0xf bank_mask:0xf bound_ctrl:1
	v_cndmask_b32_e64 v212, v210, v211, s[8:9]
	v_cndmask_b32_e64 v210, v211, v210, s[8:9]
	v_add_f32_dpp v173, v173, v173 quad_perm:[2,3,0,1] row_mask:0xf bank_mask:0xf bound_ctrl:1
	v_add_f32_dpp v174, v172, v172 quad_perm:[2,3,0,1] row_mask:0xf bank_mask:0xf bound_ctrl:1
	v_add_f32_dpp v210, v212, v210 quad_perm:[2,3,0,1] row_mask:0xf bank_mask:0xf bound_ctrl:1
	v_add_f32_dpp v172, v173, v173 row_ror:4 row_mask:0xf bank_mask:0xf bound_ctrl:1
	v_add_f32_dpp v173, v174, v174 row_ror:4 row_mask:0xf bank_mask:0xf bound_ctrl:1
	v_mov_b32_e32 v174, v177
	v_mov_b32_e32 v175, v177
	v_add_f32_dpp v210, v210, v210 row_ror:4 row_mask:0xf bank_mask:0xf bound_ctrl:1
	v_mov_b32_e32 v211, v177
	v_mov_b32_dpp v174, v172 row_ror:8 row_mask:0xf bank_mask:0xf
	v_mov_b32_dpp v175, v173 row_ror:8 row_mask:0xf bank_mask:0xf
	v_mov_b32_dpp v211, v210 row_ror:8 row_mask:0xf bank_mask:0xf
	s_and_saveexec_b64 s[78:79], s[10:11]
	v_add_f32_e32 v210, v210, v211
	ds_write_b32 v245, v210 offset:1024
	s_or_b64 exec, exec, s[78:79]
	v_pk_mul_f32 v[170:171], v[152:153], v[170:171]
	v_pk_mul_f32 v[166:167], v[154:155], v[166:167]
	v_pk_mul_f32 v[152:153], v[152:153], v[168:169]
	v_pk_mul_f32 v[154:155], v[154:155], v[164:165]
	v_pk_fma_f32 v[170:171], v[156:157], v[112:113], v[170:171] op_sel_hi:[1,0,1]
	v_pk_fma_f32 v[166:167], v[158:159], v[112:113], v[166:167] op_sel_hi:[1,0,1]
	v_pk_fma_f32 v[152:153], v[156:157], v[112:113], v[152:153] op_sel:[0,1,0]
	v_pk_fma_f32 v[112:113], v[158:159], v[112:113], v[154:155] op_sel:[0,1,0]
	v_add_f32_e32 v154, v172, v174
	v_add_f32_e32 v156, v173, v175
	v_pk_fma_f32 v[158:159], v[144:145], v[154:155], v[170:171] op_sel_hi:[1,0,1] neg_lo:[1,0,0] neg_hi:[1,0,0]
	v_pk_fma_f32 v[154:155], v[146:147], v[154:155], v[166:167] op_sel_hi:[1,0,1] neg_lo:[1,0,0] neg_hi:[1,0,0]
	v_pk_fma_f32 v[112:113], v[146:147], v[156:157], v[112:113] op_sel_hi:[1,0,1] neg_lo:[1,0,0] neg_hi:[1,0,0]
	s_waitcnt lgkmcnt(12)
	v_pk_mul_f32 v[146:147], v[150:151], v[154:155]
	v_pk_fma_f32 v[144:145], v[144:145], v[156:157], v[152:153] op_sel_hi:[1,0,1] neg_lo:[1,0,0] neg_hi:[1,0,0]
	v_pk_fma_f32 v[146:147], v[148:149], v[158:159], v[146:147]
	v_pk_mul_f32 v[150:151], v[150:151], v[112:113]
	v_add_f32_e32 v212, v146, v147
	v_pk_mul_f32 v[146:147], v[126:127], v[154:155]
	v_pk_mul_f32 v[126:127], v[126:127], v[112:113]
	v_pk_fma_f32 v[146:147], v[124:125], v[158:159], v[146:147]
	v_pk_fma_f32 v[124:125], v[124:125], v[144:145], v[126:127]
	v_add_f32_e32 v146, v146, v147
	v_add_f32_e32 v147, v124, v125
	v_pk_mul_f32 v[124:125], v[116:117], v[158:159]
	v_pk_mul_f32 v[126:127], v[118:119], v[154:155]
	v_pk_mul_f32 v[116:117], v[116:117], v[144:145]
	v_pk_mul_f32 v[112:113], v[118:119], v[112:113]
	v_pk_fma_f32 v[124:125], v[120:121], v[114:115], v[124:125] op_sel_hi:[1,0,1]
	v_pk_fma_f32 v[126:127], v[122:123], v[114:115], v[126:127] op_sel_hi:[1,0,1]
	v_pk_fma_f32 v[116:117], v[120:121], v[114:115], v[116:117] op_sel:[0,1,0]
	v_pk_fma_f32 v[112:113], v[122:123], v[114:115], v[112:113] op_sel:[0,1,0]
	v_add_f32_dpp v114, v146, v146 quad_perm:[1,0,3,2] row_mask:0xf bank_mask:0xf bound_ctrl:1
	v_add_f32_dpp v115, v147, v147 quad_perm:[1,0,3,2] row_mask:0xf bank_mask:0xf bound_ctrl:1
	v_pk_fma_f32 v[148:149], v[148:149], v[144:145], v[150:151]
	v_add_f32_dpp v114, v114, v114 quad_perm:[2,3,0,1] row_mask:0xf bank_mask:0xf bound_ctrl:1
	v_add_f32_dpp v115, v115, v115 quad_perm:[2,3,0,1] row_mask:0xf bank_mask:0xf bound_ctrl:1
	v_add_f32_e32 v213, v148, v149
	v_add_f32_dpp v114, v114, v114 row_ror:4 row_mask:0xf bank_mask:0xf bound_ctrl:1
	v_add_f32_dpp v115, v115, v115 row_ror:4 row_mask:0xf bank_mask:0xf bound_ctrl:1
	s_nop 0
	v_add_f32_dpp v114, v114, v114 row_ror:8 row_mask:0xf bank_mask:0xf bound_ctrl:1
	v_add_f32_dpp v118, v115, v115 row_ror:8 row_mask:0xf bank_mask:0xf bound_ctrl:1
	v_pk_fma_f32 v[170:171], v[102:103], v[114:115], v[126:127] op_sel_hi:[1,0,1] neg_lo:[1,0,0] neg_hi:[1,0,0]
	v_pk_fma_f32 v[168:169], v[102:103], v[118:119], v[112:113] op_sel_hi:[1,0,1] neg_lo:[1,0,0] neg_hi:[1,0,0]
	v_pk_fma_f32 v[174:175], v[100:101], v[114:115], v[124:125] op_sel_hi:[1,0,1] neg_lo:[1,0,0] neg_hi:[1,0,0]
	v_pk_fma_f32 v[172:173], v[100:101], v[118:119], v[116:117] op_sel_hi:[1,0,1] neg_lo:[1,0,0] neg_hi:[1,0,0]
	s_waitcnt lgkmcnt(11)
	v_pk_mul_f32 v[100:101], v[106:107], v[170:171]
	v_pk_mul_f32 v[102:103], v[106:107], v[168:169]
	v_pk_fma_f32 v[100:101], v[104:105], v[174:175], v[100:101]
	v_pk_fma_f32 v[102:103], v[104:105], v[172:173], v[102:103]
	v_add_f32_e32 v214, v100, v101
	v_add_f32_e32 v215, v102, v103
	ds_read2_b64 v[112:115], v247 offset0:224 offset1:240
	ds_read_b128 v[152:155], v244 offset:3584
	ds_read_b128 v[116:119], v244 offset:3840
	ds_read_b128 v[164:167], v244 offset:11776
	ds_read_b128 v[124:127], v244 offset:12032
	ds_read_b128 v[144:147], v244 offset:19968
	ds_read_b128 v[100:103], v244 offset:20224
	ds_read_b128 v[156:159], v244 offset:28160
	ds_read_b128 v[120:123], v244 offset:28416
	ds_read_b128 v[148:151], v244 offset:36352
	ds_read_b128 v[104:107], v244 offset:36608
	s_waitcnt lgkmcnt(14)
	v_pk_mul_f32 v[210:211], v[162:163], v[170:171]
	v_pk_mul_f32 v[162:163], v[162:163], v[168:169]
	v_pk_fma_f32 v[210:211], v[160:161], v[174:175], v[210:211]
	v_pk_fma_f32 v[160:161], v[160:161], v[172:173], v[162:163]
	v_add_f32_e32 v162, v210, v211
	v_cndmask_b32_e64 v210, v212, v213, s[6:7]
	v_cndmask_b32_e64 v211, v214, v215, s[6:7]
	v_cndmask_b32_e64 v212, v213, v212, s[6:7]
	v_cndmask_b32_e64 v213, v215, v214, s[6:7]
	v_add_f32_e32 v160, v160, v161
	v_add_f32_dpp v210, v210, v212 quad_perm:[1,0,3,2] row_mask:0xf bank_mask:0xf bound_ctrl:1
	v_add_f32_dpp v211, v211, v213 quad_perm:[1,0,3,2] row_mask:0xf bank_mask:0xf bound_ctrl:1
	v_add_f32_dpp v161, v162, v162 quad_perm:[1,0,3,2] row_mask:0xf bank_mask:0xf bound_ctrl:1
	v_add_f32_dpp v160, v160, v160 quad_perm:[1,0,3,2] row_mask:0xf bank_mask:0xf bound_ctrl:1
	v_cndmask_b32_e64 v212, v210, v211, s[8:9]
	v_cndmask_b32_e64 v210, v211, v210, s[8:9]
	v_add_f32_dpp v161, v161, v161 quad_perm:[2,3,0,1] row_mask:0xf bank_mask:0xf bound_ctrl:1
	v_add_f32_dpp v162, v160, v160 quad_perm:[2,3,0,1] row_mask:0xf bank_mask:0xf bound_ctrl:1
	v_add_f32_dpp v210, v212, v210 quad_perm:[2,3,0,1] row_mask:0xf bank_mask:0xf bound_ctrl:1
	v_add_f32_dpp v160, v161, v161 row_ror:4 row_mask:0xf bank_mask:0xf bound_ctrl:1
	v_add_f32_dpp v161, v162, v162 row_ror:4 row_mask:0xf bank_mask:0xf bound_ctrl:1
	v_mov_b32_e32 v162, 0
	v_mov_b32_e32 v163, 0
	v_add_f32_dpp v210, v210, v210 row_ror:4 row_mask:0xf bank_mask:0xf bound_ctrl:1
	v_mov_b32_e32 v211, 0
	v_mov_b32_dpp v162, v160 row_ror:8 row_mask:0xf bank_mask:0xf
	v_mov_b32_dpp v163, v161 row_ror:8 row_mask:0xf bank_mask:0xf
	v_mov_b32_dpp v211, v210 row_ror:8 row_mask:0xf bank_mask:0xf
	s_and_saveexec_b64 s[78:79], s[10:11]
	v_add_f32_e32 v210, v210, v211
	ds_write_b32 v245, v210 offset:1280
	s_or_b64 exec, exec, s[78:79]
	v_pk_mul_f32 v[174:175], v[136:137], v[174:175]
	v_pk_mul_f32 v[170:171], v[138:139], v[170:171]
	v_pk_mul_f32 v[136:137], v[136:137], v[172:173]
	v_pk_mul_f32 v[138:139], v[138:139], v[168:169]
	v_pk_fma_f32 v[174:175], v[140:141], v[88:89], v[174:175] op_sel_hi:[1,0,1]
	v_pk_fma_f32 v[170:171], v[142:143], v[88:89], v[170:171] op_sel_hi:[1,0,1]
	v_pk_fma_f32 v[136:137], v[140:141], v[88:89], v[136:137] op_sel:[0,1,0]
	v_pk_fma_f32 v[88:89], v[142:143], v[88:89], v[138:139] op_sel:[0,1,0]
	v_add_f32_e32 v138, v160, v162
	v_add_f32_e32 v140, v161, v163
	v_pk_fma_f32 v[142:143], v[128:129], v[138:139], v[174:175] op_sel_hi:[1,0,1] neg_lo:[1,0,0] neg_hi:[1,0,0]
	v_pk_fma_f32 v[138:139], v[130:131], v[138:139], v[170:171] op_sel_hi:[1,0,1] neg_lo:[1,0,0] neg_hi:[1,0,0]
	v_pk_fma_f32 v[88:89], v[130:131], v[140:141], v[88:89] op_sel_hi:[1,0,1] neg_lo:[1,0,0] neg_hi:[1,0,0]
	s_waitcnt lgkmcnt(12)
	v_pk_mul_f32 v[130:131], v[134:135], v[138:139]
	v_pk_fma_f32 v[128:129], v[128:129], v[140:141], v[136:137] op_sel_hi:[1,0,1] neg_lo:[1,0,0] neg_hi:[1,0,0]
	v_pk_fma_f32 v[130:131], v[132:133], v[142:143], v[130:131]
	v_pk_mul_f32 v[134:135], v[134:135], v[88:89]
	s_nop 0
	v_pk_fma_f32 v[132:133], v[132:133], v[128:129], v[134:135]
	v_add_f32_e32 v134, v130, v131
	v_pk_mul_f32 v[130:131], v[110:111], v[138:139]
	v_pk_mul_f32 v[110:111], v[110:111], v[88:89]
	v_pk_fma_f32 v[130:131], v[108:109], v[142:143], v[130:131]
	v_pk_fma_f32 v[108:109], v[108:109], v[128:129], v[110:111]
	v_add_f32_e32 v130, v130, v131
	v_add_f32_e32 v131, v108, v109
	v_pk_mul_f32 v[88:89], v[94:95], v[88:89]
	v_pk_mul_f32 v[110:111], v[94:95], v[138:139]
	v_pk_fma_f32 v[94:95], v[98:99], v[90:91], v[88:89] op_sel:[0,1,0]
	v_add_f32_dpp v88, v130, v130 quad_perm:[1,0,3,2] row_mask:0xf bank_mask:0xf bound_ctrl:1
	v_add_f32_dpp v89, v131, v131 quad_perm:[1,0,3,2] row_mask:0xf bank_mask:0xf bound_ctrl:1
	v_pk_mul_f32 v[108:109], v[92:93], v[142:143]
	v_add_f32_dpp v88, v88, v88 quad_perm:[2,3,0,1] row_mask:0xf bank_mask:0xf bound_ctrl:1
	v_add_f32_dpp v89, v89, v89 quad_perm:[2,3,0,1] row_mask:0xf bank_mask:0xf bound_ctrl:1
	v_pk_mul_f32 v[92:93], v[92:93], v[128:129]
	v_add_f32_dpp v88, v88, v88 row_ror:4 row_mask:0xf bank_mask:0xf bound_ctrl:1
	v_add_f32_dpp v89, v89, v89 row_ror:4 row_mask:0xf bank_mask:0xf bound_ctrl:1
	v_pk_fma_f32 v[108:109], v[96:97], v[90:91], v[108:109] op_sel_hi:[1,0,1]
	v_pk_fma_f32 v[110:111], v[98:99], v[90:91], v[110:111] op_sel_hi:[1,0,1]
	v_pk_fma_f32 v[96:97], v[96:97], v[90:91], v[92:93] op_sel:[0,1,0]
	v_add_f32_dpp v88, v88, v88 row_ror:8 row_mask:0xf bank_mask:0xf bound_ctrl:1
	v_add_f32_dpp v98, v89, v89 row_ror:8 row_mask:0xf bank_mask:0xf bound_ctrl:1
	v_pk_fma_f32 v[92:93], v[80:81], v[88:89], v[108:109] op_sel_hi:[1,0,1] neg_lo:[1,0,0] neg_hi:[1,0,0]
	v_pk_fma_f32 v[88:89], v[82:83], v[88:89], v[110:111] op_sel_hi:[1,0,1] neg_lo:[1,0,0] neg_hi:[1,0,0]
	v_pk_fma_f32 v[90:91], v[80:81], v[98:99], v[96:97] op_sel_hi:[1,0,1] neg_lo:[1,0,0] neg_hi:[1,0,0]
	v_pk_fma_f32 v[80:81], v[82:83], v[98:99], v[94:95] op_sel_hi:[1,0,1] neg_lo:[1,0,0] neg_hi:[1,0,0]
	s_waitcnt lgkmcnt(11)
	v_pk_mul_f32 v[82:83], v[86:87], v[88:89]
	v_pk_mul_f32 v[86:87], v[86:87], v[80:81]
	v_pk_fma_f32 v[82:83], v[84:85], v[92:93], v[82:83]
	v_pk_fma_f32 v[84:85], v[84:85], v[90:91], v[86:87]
	v_add_f32_e32 v86, v82, v83
	v_add_f32_e32 v87, v84, v85
	v_add_f32_e32 v132, v132, v133
	s_waitcnt lgkmcnt(7)
	v_pk_mul_f32 v[82:83], v[166:167], v[88:89]
	v_pk_mul_f32 v[84:85], v[166:167], v[80:81]
	v_pk_fma_f32 v[82:83], v[164:165], v[92:93], v[82:83]
	v_pk_fma_f32 v[84:85], v[164:165], v[90:91], v[84:85]
	v_cndmask_b32_e64 v94, v134, v132, s[6:7]
	v_cndmask_b32_e64 v95, v86, v87, s[6:7]
	v_cndmask_b32_e64 v96, v132, v134, s[6:7]
	v_cndmask_b32_e64 v86, v87, v86, s[6:7]
	v_add_f32_e32 v82, v82, v83
	v_add_f32_e32 v83, v84, v85
	v_add_f32_dpp v87, v94, v96 quad_perm:[1,0,3,2] row_mask:0xf bank_mask:0xf bound_ctrl:1
	v_add_f32_dpp v86, v95, v86 quad_perm:[1,0,3,2] row_mask:0xf bank_mask:0xf bound_ctrl:1
	v_add_f32_dpp v82, v82, v82 quad_perm:[1,0,3,2] row_mask:0xf bank_mask:0xf bound_ctrl:1
	v_add_f32_dpp v83, v83, v83 quad_perm:[1,0,3,2] row_mask:0xf bank_mask:0xf bound_ctrl:1
	v_cndmask_b32_e64 v94, v87, v86, s[8:9]
	v_cndmask_b32_e64 v86, v86, v87, s[8:9]
	v_add_f32_dpp v82, v82, v82 quad_perm:[2,3,0,1] row_mask:0xf bank_mask:0xf bound_ctrl:1
	v_add_f32_dpp v83, v83, v83 quad_perm:[2,3,0,1] row_mask:0xf bank_mask:0xf bound_ctrl:1
	v_add_f32_dpp v86, v94, v86 quad_perm:[2,3,0,1] row_mask:0xf bank_mask:0xf bound_ctrl:1
	v_add_f32_dpp v82, v82, v82 row_ror:4 row_mask:0xf bank_mask:0xf bound_ctrl:1
	v_add_f32_dpp v83, v83, v83 row_ror:4 row_mask:0xf bank_mask:0xf bound_ctrl:1
	v_mov_b32_e32 v84, 0
	v_mov_b32_e32 v85, 0
	v_add_f32_dpp v86, v86, v86 row_ror:4 row_mask:0xf bank_mask:0xf bound_ctrl:1
	v_mov_b32_e32 v87, 0
	v_mov_b32_dpp v84, v82 row_ror:8 row_mask:0xf bank_mask:0xf
	v_mov_b32_dpp v85, v83 row_ror:8 row_mask:0xf bank_mask:0xf
	v_mov_b32_dpp v87, v86 row_ror:8 row_mask:0xf bank_mask:0xf
	s_and_saveexec_b64 s[78:79], s[10:11]
	v_add_f32_e32 v86, v86, v87
	ds_write_b32 v245, v86 offset:1536
	s_or_b64 exec, exec, s[78:79]
	v_pk_mul_f32 v[86:87], v[152:153], v[92:93]
	v_pk_mul_f32 v[88:89], v[154:155], v[88:89]
	v_pk_mul_f32 v[80:81], v[154:155], v[80:81]
	s_waitcnt lgkmcnt(3)
	v_pk_fma_f32 v[86:87], v[156:157], v[112:113], v[86:87] op_sel_hi:[1,0,1]
	v_pk_fma_f32 v[88:89], v[158:159], v[112:113], v[88:89] op_sel_hi:[1,0,1]
	v_pk_mul_f32 v[90:91], v[152:153], v[90:91]
	v_pk_fma_f32 v[80:81], v[158:159], v[112:113], v[80:81] op_sel:[0,1,0]
	v_add_f32_e32 v82, v82, v84
	v_add_f32_e32 v84, v83, v85
	v_pk_fma_f32 v[90:91], v[156:157], v[112:113], v[90:91] op_sel:[0,1,0]
	v_pk_fma_f32 v[86:87], v[144:145], v[82:83], v[86:87] op_sel_hi:[1,0,1] neg_lo:[1,0,0] neg_hi:[1,0,0]
	v_pk_fma_f32 v[82:83], v[146:147], v[82:83], v[88:89] op_sel_hi:[1,0,1] neg_lo:[1,0,0] neg_hi:[1,0,0]
	v_pk_fma_f32 v[80:81], v[146:147], v[84:85], v[80:81] op_sel_hi:[1,0,1] neg_lo:[1,0,0] neg_hi:[1,0,0]
	v_pk_fma_f32 v[88:89], v[144:145], v[84:85], v[90:91] op_sel_hi:[1,0,1] neg_lo:[1,0,0] neg_hi:[1,0,0]
	s_waitcnt lgkmcnt(1)
	v_pk_mul_f32 v[84:85], v[150:151], v[82:83]
	v_pk_mul_f32 v[90:91], v[150:151], v[80:81]
	v_pk_fma_f32 v[84:85], v[148:149], v[86:87], v[84:85]
	v_pk_fma_f32 v[90:91], v[148:149], v[88:89], v[90:91]
	v_add_f32_e32 v96, v84, v85
	v_add_f32_e32 v97, v90, v91
	v_pk_mul_f32 v[84:85], v[126:127], v[82:83]
	v_pk_mul_f32 v[90:91], v[126:127], v[80:81]
	v_pk_fma_f32 v[84:85], v[124:125], v[86:87], v[84:85]
	v_pk_fma_f32 v[90:91], v[124:125], v[88:89], v[90:91]
	v_add_f32_e32 v92, v84, v85
	v_add_f32_e32 v90, v90, v91
	v_pk_mul_f32 v[84:85], v[116:117], v[86:87]
	v_pk_mul_f32 v[86:87], v[116:117], v[88:89]
	v_add_f32_dpp v88, v92, v92 quad_perm:[1,0,3,2] row_mask:0xf bank_mask:0xf bound_ctrl:1
	v_add_f32_dpp v89, v90, v90 quad_perm:[1,0,3,2] row_mask:0xf bank_mask:0xf bound_ctrl:1
	v_pk_mul_f32 v[82:83], v[118:119], v[82:83]
	v_add_f32_dpp v88, v88, v88 quad_perm:[2,3,0,1] row_mask:0xf bank_mask:0xf bound_ctrl:1
	v_add_f32_dpp v89, v89, v89 quad_perm:[2,3,0,1] row_mask:0xf bank_mask:0xf bound_ctrl:1
	v_pk_mul_f32 v[80:81], v[118:119], v[80:81]
	v_add_f32_dpp v88, v88, v88 row_ror:4 row_mask:0xf bank_mask:0xf bound_ctrl:1
	v_add_f32_dpp v89, v89, v89 row_ror:4 row_mask:0xf bank_mask:0xf bound_ctrl:1
	v_pk_fma_f32 v[84:85], v[120:121], v[114:115], v[84:85] op_sel_hi:[1,0,1]
	v_pk_fma_f32 v[82:83], v[122:123], v[114:115], v[82:83] op_sel_hi:[1,0,1]
	v_pk_fma_f32 v[86:87], v[120:121], v[114:115], v[86:87] op_sel:[0,1,0]
	v_pk_fma_f32 v[80:81], v[122:123], v[114:115], v[80:81] op_sel:[0,1,0]
	v_add_f32_dpp v90, v88, v88 row_ror:8 row_mask:0xf bank_mask:0xf bound_ctrl:1
	v_add_f32_dpp v94, v89, v89 row_ror:8 row_mask:0xf bank_mask:0xf bound_ctrl:1
	v_pk_fma_f32 v[88:89], v[100:101], v[90:91], v[84:85] op_sel_hi:[1,0,1] neg_lo:[1,0,0] neg_hi:[1,0,0]
	v_pk_fma_f32 v[90:91], v[102:103], v[90:91], v[82:83] op_sel_hi:[1,0,1] neg_lo:[1,0,0] neg_hi:[1,0,0]
	v_pk_fma_f32 v[92:93], v[100:101], v[94:95], v[86:87] op_sel_hi:[1,0,1] neg_lo:[1,0,0] neg_hi:[1,0,0]
	v_pk_fma_f32 v[94:95], v[102:103], v[94:95], v[80:81] op_sel_hi:[1,0,1] neg_lo:[1,0,0] neg_hi:[1,0,0]
	s_waitcnt lgkmcnt(0)
	v_pk_mul_f32 v[80:81], v[106:107], v[90:91]
	v_pk_mul_f32 v[82:83], v[106:107], v[94:95]
	v_pk_fma_f32 v[80:81], v[104:105], v[88:89], v[80:81]
	v_pk_fma_f32 v[82:83], v[104:105], v[92:93], v[82:83]
	v_add_f32_e32 v80, v80, v81
	v_add_f32_e32 v81, v82, v83
	v_cndmask_b32_e64 v82, v96, v97, s[6:7]
	v_cndmask_b32_e64 v83, v80, v81, s[6:7]
	v_cndmask_b32_e64 v84, v97, v96, s[6:7]
	v_cndmask_b32_e64 v80, v81, v80, s[6:7]
	s_nop 0
	v_add_f32_dpp v81, v82, v84 quad_perm:[1,0,3,2] row_mask:0xf bank_mask:0xf bound_ctrl:1
	v_add_f32_dpp v80, v83, v80 quad_perm:[1,0,3,2] row_mask:0xf bank_mask:0xf bound_ctrl:1
	v_cndmask_b32_e64 v82, v81, v80, s[8:9]
	v_cndmask_b32_e64 v80, v80, v81, s[8:9]
	v_mov_b32_e32 v81, 0
	s_nop 0
	v_add_f32_dpp v80, v82, v80 quad_perm:[2,3,0,1] row_mask:0xf bank_mask:0xf bound_ctrl:1
	s_nop 1
	v_add_f32_dpp v80, v80, v80 row_ror:4 row_mask:0xf bank_mask:0xf bound_ctrl:1
	s_nop 1
	v_mov_b32_dpp v81, v80 row_ror:8 row_mask:0xf bank_mask:0xf
	s_and_saveexec_b64 s[78:79], s[10:11]
	v_add3_u32 v82, v176, v239, v197
	v_add_f32_e32 v80, v80, v81
	ds_write_b32 v82, v80 offset:1792
	s_or_b64 exec, exec, s[78:79]
	s_ashr_i32 s28, s24, 5
	s_add_i32 s29, s24, 0xffffff00
	s_not_b32 s28, s28
	s_lshr_b32 s29, s29, 5
	s_cmpk_lt_i32 s24, 0x100
	s_cselect_b32 s28, s28, s29
	s_ashr_i32 s29, s28, 31
	s_lshl_b32 s24, s24, 5
	s_lshl_b64 s[28:29], s[28:29], 10
	s_and_b32 s24, s24, 0x3e0
	s_or_b32 s24, s28, s24
	v_mov_b32_e32 v81, s29
	v_or_b32_e32 v80, s24, v192
	v_lshlrev_b64 v[80:81], 8, v[80:81]
	v_lshl_add_u64 v[80:81], v[198:199], 0, v[80:81]
	global_store_dwordx4 v[80:81], v[88:91], off
	global_store_dwordx4 v[80:81], v[92:95], off offset:256
	s_add_i32 s24, s70, s5
	s_cmpk_gt_i32 s24, 0x10ff
	v_add_u32_e32 v168, 0xa800, v246
	s_cbranch_scc0 .LBB0_328

.LBB0_328:
	ds_read2_b64 v[80:83], v168 offset1:16
	ds_read_b128 v[84:87], v244 offset:37120
	ds_read_b128 v[88:91], v244 offset:36864
	ds_read_b128 v[100:103], v244 offset:28928
	ds_read_b128 v[120:123], v244 offset:28672
	ds_read_b128 v[124:127], v244 offset:20736
	ds_read_b128 v[128:131], v244 offset:20480
	ds_read_b128 v[132:135], v244 offset:12544
	ds_read_b128 v[152:155], v244 offset:12288
	ds_read_b128 v[156:159], v244 offset:4352
	ds_read_b128 v[160:163], v244 offset:4096
	ds_read2_b64 v[104:107], v168 offset0:32 offset1:48
	ds_read_b128 v[144:147], v244 offset:4608
	ds_read_b128 v[108:111], v244 offset:4864
	ds_read_b128 v[164:167], v244 offset:12800
	ds_read_b128 v[116:119], v244 offset:13056
	ds_read_b128 v[136:139], v244 offset:20992
	ds_read_b128 v[92:95], v244 offset:21248
	ds_read_b128 v[148:151], v244 offset:29184
	ds_read_b128 v[112:115], v244 offset:29440
	ds_read_b128 v[140:143], v244 offset:37376
	ds_read_b128 v[96:99], v244 offset:37632
	s_waitcnt lgkmcnt(13)
	v_pk_mul_f32 v[170:171], v[74:75], v[154:155]
	v_pk_mul_f32 v[154:155], v[78:79], v[154:155]
	v_pk_fma_f32 v[170:171], v[72:73], v[152:153], v[170:171]
	v_pk_fma_f32 v[152:153], v[76:77], v[152:153], v[154:155]
	v_add_f32_e32 v154, v170, v171
	v_add_f32_e32 v152, v152, v153
	s_waitcnt lgkmcnt(11)
	v_pk_mul_f32 v[76:77], v[76:77], v[160:161]
	v_add_f32_dpp v153, v154, v154 quad_perm:[1,0,3,2] row_mask:0xf bank_mask:0xf bound_ctrl:1
	v_add_f32_dpp v152, v152, v152 quad_perm:[1,0,3,2] row_mask:0xf bank_mask:0xf bound_ctrl:1
	v_pk_mul_f32 v[72:73], v[72:73], v[160:161]
	v_add_f32_dpp v153, v153, v153 quad_perm:[2,3,0,1] row_mask:0xf bank_mask:0xf bound_ctrl:1
	v_add_f32_dpp v152, v152, v152 quad_perm:[2,3,0,1] row_mask:0xf bank_mask:0xf bound_ctrl:1
	v_pk_mul_f32 v[74:75], v[74:75], v[162:163]
	v_add_f32_dpp v154, v153, v153 row_ror:4 row_mask:0xf bank_mask:0xf bound_ctrl:1
	v_add_f32_dpp v152, v152, v152 row_ror:4 row_mask:0xf bank_mask:0xf bound_ctrl:1
	v_pk_fma_f32 v[76:77], v[80:81], v[120:121], v[76:77] op_sel:[1,0,0]
	v_pk_mul_f32 v[78:79], v[78:79], v[162:163]
	v_pk_fma_f32 v[72:73], v[80:81], v[120:121], v[72:73] op_sel_hi:[0,1,1]
	v_add_f32_dpp v120, v154, v154 row_ror:8 row_mask:0xf bank_mask:0xf bound_ctrl:1
	v_pk_fma_f32 v[74:75], v[80:81], v[122:123], v[74:75] op_sel_hi:[0,1,1]
	v_add_f32_dpp v152, v152, v152 row_ror:8 row_mask:0xf bank_mask:0xf bound_ctrl:1
	v_pk_fma_f32 v[78:79], v[80:81], v[122:123], v[78:79] op_sel:[1,0,0]
	v_pk_fma_f32 v[74:75], v[130:131], v[120:121], v[74:75] op_sel_hi:[1,0,1] neg_lo:[1,0,0] neg_hi:[1,0,0]
	v_pk_fma_f32 v[78:79], v[130:131], v[152:153], v[78:79] op_sel_hi:[1,0,1] neg_lo:[1,0,0] neg_hi:[1,0,0]
	v_pk_fma_f32 v[72:73], v[128:129], v[120:121], v[72:73] op_sel_hi:[1,0,1] neg_lo:[1,0,0] neg_hi:[1,0,0]
	v_pk_mul_f32 v[80:81], v[90:91], v[74:75]
	v_pk_fma_f32 v[76:77], v[128:129], v[152:153], v[76:77] op_sel_hi:[1,0,1] neg_lo:[1,0,0] neg_hi:[1,0,0]
	v_pk_mul_f32 v[152:153], v[90:91], v[78:79]
	v_pk_fma_f32 v[80:81], v[88:89], v[72:73], v[80:81]
	v_pk_fma_f32 v[152:153], v[88:89], v[76:77], v[152:153]
	v_add_f32_e32 v172, v80, v81
	v_pk_mul_f32 v[80:81], v[134:135], v[74:75]
	v_pk_mul_f32 v[88:89], v[134:135], v[78:79]
	v_pk_fma_f32 v[80:81], v[132:133], v[72:73], v[80:81]
	v_pk_fma_f32 v[88:89], v[132:133], v[76:77], v[88:89]
	v_add_f32_e32 v80, v80, v81
	v_add_f32_e32 v81, v88, v89
	v_pk_mul_f32 v[72:73], v[156:157], v[72:73]
	v_add_f32_dpp v80, v80, v80 quad_perm:[1,0,3,2] row_mask:0xf bank_mask:0xf bound_ctrl:1
	v_add_f32_dpp v81, v81, v81 quad_perm:[1,0,3,2] row_mask:0xf bank_mask:0xf bound_ctrl:1
	v_pk_mul_f32 v[74:75], v[158:159], v[74:75]
	v_add_f32_dpp v80, v80, v80 quad_perm:[2,3,0,1] row_mask:0xf bank_mask:0xf bound_ctrl:1
	v_add_f32_dpp v81, v81, v81 quad_perm:[2,3,0,1] row_mask:0xf bank_mask:0xf bound_ctrl:1
	v_pk_mul_f32 v[76:77], v[156:157], v[76:77]
	v_pk_mul_f32 v[78:79], v[158:159], v[78:79]
	v_add_f32_dpp v80, v80, v80 row_ror:4 row_mask:0xf bank_mask:0xf bound_ctrl:1
	v_add_f32_dpp v81, v81, v81 row_ror:4 row_mask:0xf bank_mask:0xf bound_ctrl:1
	v_pk_fma_f32 v[72:73], v[82:83], v[100:101], v[72:73] op_sel_hi:[0,1,1]
	v_pk_fma_f32 v[74:75], v[82:83], v[102:103], v[74:75] op_sel_hi:[0,1,1]
	v_pk_fma_f32 v[76:77], v[82:83], v[100:101], v[76:77] op_sel:[1,0,0]
	v_pk_fma_f32 v[78:79], v[82:83], v[102:103], v[78:79] op_sel:[1,0,0]
	v_add_f32_dpp v80, v80, v80 row_ror:8 row_mask:0xf bank_mask:0xf bound_ctrl:1
	v_add_f32_dpp v82, v81, v81 row_ror:8 row_mask:0xf bank_mask:0xf bound_ctrl:1
	v_pk_fma_f32 v[158:159], v[126:127], v[80:81], v[74:75] op_sel_hi:[1,0,1] neg_lo:[1,0,0] neg_hi:[1,0,0]
	v_pk_fma_f32 v[156:157], v[126:127], v[82:83], v[78:79] op_sel_hi:[1,0,1] neg_lo:[1,0,0] neg_hi:[1,0,0]
	v_pk_fma_f32 v[162:163], v[124:125], v[80:81], v[72:73] op_sel_hi:[1,0,1] neg_lo:[1,0,0] neg_hi:[1,0,0]
	v_pk_fma_f32 v[160:161], v[124:125], v[82:83], v[76:77] op_sel_hi:[1,0,1] neg_lo:[1,0,0] neg_hi:[1,0,0]
	v_pk_mul_f32 v[72:73], v[86:87], v[158:159]
	v_pk_mul_f32 v[74:75], v[86:87], v[156:157]
	v_add_f32_e32 v169, v152, v153
	v_pk_fma_f32 v[72:73], v[84:85], v[162:163], v[72:73]
	v_pk_fma_f32 v[74:75], v[84:85], v[160:161], v[74:75]
	v_add_f32_e32 v173, v72, v73
	v_add_f32_e32 v174, v74, v75
	ds_read2_b64 v[80:83], v168 offset0:64 offset1:80
	ds_read_b128 v[128:131], v244 offset:5120
	ds_read_b128 v[84:87], v244 offset:5376
	ds_read_b128 v[152:155], v244 offset:13312
	ds_read_b128 v[100:103], v244 offset:13568
	ds_read_b128 v[120:123], v244 offset:21504
	ds_read_b128 v[72:75], v244 offset:21760
	ds_read_b128 v[132:135], v244 offset:29696
	ds_read_b128 v[88:91], v244 offset:29952
	ds_read_b128 v[124:127], v244 offset:37888
	ds_read_b128 v[76:79], v244 offset:38144
	s_waitcnt lgkmcnt(14)
	v_pk_mul_f32 v[170:171], v[166:167], v[158:159]
	v_pk_mul_f32 v[166:167], v[166:167], v[156:157]
	v_pk_fma_f32 v[170:171], v[164:165], v[162:163], v[170:171]
	v_pk_fma_f32 v[164:165], v[164:165], v[160:161], v[166:167]
	v_add_f32_e32 v166, v170, v171
	v_cndmask_b32_e64 v170, v172, v169, s[6:7]
	v_cndmask_b32_e64 v171, v173, v174, s[6:7]
	v_cndmask_b32_e64 v169, v169, v172, s[6:7]
	v_cndmask_b32_e64 v172, v174, v173, s[6:7]
	v_add_f32_e32 v164, v164, v165
	v_add_f32_dpp v169, v170, v169 quad_perm:[1,0,3,2] row_mask:0xf bank_mask:0xf bound_ctrl:1
	v_add_f32_dpp v170, v171, v172 quad_perm:[1,0,3,2] row_mask:0xf bank_mask:0xf bound_ctrl:1
	v_add_f32_dpp v165, v166, v166 quad_perm:[1,0,3,2] row_mask:0xf bank_mask:0xf bound_ctrl:1
	v_add_f32_dpp v164, v164, v164 quad_perm:[1,0,3,2] row_mask:0xf bank_mask:0xf bound_ctrl:1
	v_cndmask_b32_e64 v171, v169, v170, s[8:9]
	v_cndmask_b32_e64 v169, v170, v169, s[8:9]
	v_add_f32_dpp v165, v165, v165 quad_perm:[2,3,0,1] row_mask:0xf bank_mask:0xf bound_ctrl:1
	v_add_f32_dpp v166, v164, v164 quad_perm:[2,3,0,1] row_mask:0xf bank_mask:0xf bound_ctrl:1
	v_add_f32_dpp v169, v171, v169 quad_perm:[2,3,0,1] row_mask:0xf bank_mask:0xf bound_ctrl:1
	v_add_f32_dpp v164, v165, v165 row_ror:4 row_mask:0xf bank_mask:0xf bound_ctrl:1
	v_add_f32_dpp v165, v166, v166 row_ror:4 row_mask:0xf bank_mask:0xf bound_ctrl:1
	v_mov_b32_e32 v166, v177
	v_mov_b32_e32 v167, v177
	v_add_f32_dpp v169, v169, v169 row_ror:4 row_mask:0xf bank_mask:0xf bound_ctrl:1
	v_mov_b32_e32 v170, v177
	v_mov_b32_dpp v166, v164 row_ror:8 row_mask:0xf bank_mask:0xf
	v_mov_b32_dpp v167, v165 row_ror:8 row_mask:0xf bank_mask:0xf
	v_mov_b32_dpp v170, v169 row_ror:8 row_mask:0xf bank_mask:0xf
	s_and_saveexec_b64 s[78:79], s[10:11]
	v_add_f32_e32 v169, v169, v170
	ds_write_b32 v245, v169 offset:2048
	s_or_b64 exec, exec, s[78:79]
	v_pk_mul_f32 v[162:163], v[144:145], v[162:163]
	v_pk_mul_f32 v[158:159], v[146:147], v[158:159]
	v_pk_mul_f32 v[144:145], v[144:145], v[160:161]
	v_pk_mul_f32 v[146:147], v[146:147], v[156:157]
	v_pk_fma_f32 v[162:163], v[148:149], v[104:105], v[162:163] op_sel_hi:[1,0,1]
	v_pk_fma_f32 v[158:159], v[150:151], v[104:105], v[158:159] op_sel_hi:[1,0,1]
	v_pk_fma_f32 v[144:145], v[148:149], v[104:105], v[144:145] op_sel:[0,1,0]
	v_pk_fma_f32 v[104:105], v[150:151], v[104:105], v[146:147] op_sel:[0,1,0]
	v_add_f32_e32 v146, v164, v166
	v_add_f32_e32 v148, v165, v167
	v_pk_fma_f32 v[150:151], v[136:137], v[146:147], v[162:163] op_sel_hi:[1,0,1] neg_lo:[1,0,0] neg_hi:[1,0,0]
	v_pk_fma_f32 v[146:147], v[138:139], v[146:147], v[158:159] op_sel_hi:[1,0,1] neg_lo:[1,0,0] neg_hi:[1,0,0]
	v_pk_fma_f32 v[104:105], v[138:139], v[148:149], v[104:105] op_sel_hi:[1,0,1] neg_lo:[1,0,0] neg_hi:[1,0,0]
	s_waitcnt lgkmcnt(12)
	v_pk_mul_f32 v[138:139], v[142:143], v[146:147]
	v_pk_fma_f32 v[136:137], v[136:137], v[148:149], v[144:145] op_sel_hi:[1,0,1] neg_lo:[1,0,0] neg_hi:[1,0,0]
	v_pk_fma_f32 v[138:139], v[140:141], v[150:151], v[138:139]
	v_pk_mul_f32 v[142:143], v[142:143], v[104:105]
	v_add_f32_e32 v169, v138, v139
	v_pk_mul_f32 v[138:139], v[118:119], v[146:147]
	v_pk_mul_f32 v[118:119], v[118:119], v[104:105]
	v_pk_fma_f32 v[138:139], v[116:117], v[150:151], v[138:139]
	v_pk_fma_f32 v[116:117], v[116:117], v[136:137], v[118:119]
	v_add_f32_e32 v138, v138, v139
	v_add_f32_e32 v139, v116, v117
	v_pk_mul_f32 v[116:117], v[108:109], v[150:151]
	v_pk_mul_f32 v[118:119], v[110:111], v[146:147]
	v_pk_mul_f32 v[108:109], v[108:109], v[136:137]
	v_pk_mul_f32 v[104:105], v[110:111], v[104:105]
	v_pk_fma_f32 v[116:117], v[112:113], v[106:107], v[116:117] op_sel_hi:[1,0,1]
	v_pk_fma_f32 v[118:119], v[114:115], v[106:107], v[118:119] op_sel_hi:[1,0,1]
	v_pk_fma_f32 v[108:109], v[112:113], v[106:107], v[108:109] op_sel:[0,1,0]
	v_pk_fma_f32 v[104:105], v[114:115], v[106:107], v[104:105] op_sel:[0,1,0]
	v_add_f32_dpp v106, v138, v138 quad_perm:[1,0,3,2] row_mask:0xf bank_mask:0xf bound_ctrl:1
	v_add_f32_dpp v107, v139, v139 quad_perm:[1,0,3,2] row_mask:0xf bank_mask:0xf bound_ctrl:1
	v_pk_fma_f32 v[140:141], v[140:141], v[136:137], v[142:143]
	v_add_f32_dpp v106, v106, v106 quad_perm:[2,3,0,1] row_mask:0xf bank_mask:0xf bound_ctrl:1
	v_add_f32_dpp v107, v107, v107 quad_perm:[2,3,0,1] row_mask:0xf bank_mask:0xf bound_ctrl:1
	v_add_f32_e32 v172, v140, v141
	v_add_f32_dpp v106, v106, v106 row_ror:4 row_mask:0xf bank_mask:0xf bound_ctrl:1
	v_add_f32_dpp v107, v107, v107 row_ror:4 row_mask:0xf bank_mask:0xf bound_ctrl:1
	s_nop 0
	v_add_f32_dpp v106, v106, v106 row_ror:8 row_mask:0xf bank_mask:0xf bound_ctrl:1
	v_add_f32_dpp v110, v107, v107 row_ror:8 row_mask:0xf bank_mask:0xf bound_ctrl:1
	v_pk_fma_f32 v[162:163], v[94:95], v[106:107], v[118:119] op_sel_hi:[1,0,1] neg_lo:[1,0,0] neg_hi:[1,0,0]
	v_pk_fma_f32 v[160:161], v[94:95], v[110:111], v[104:105] op_sel_hi:[1,0,1] neg_lo:[1,0,0] neg_hi:[1,0,0]
	v_pk_fma_f32 v[166:167], v[92:93], v[106:107], v[116:117] op_sel_hi:[1,0,1] neg_lo:[1,0,0] neg_hi:[1,0,0]
	v_pk_fma_f32 v[164:165], v[92:93], v[110:111], v[108:109] op_sel_hi:[1,0,1] neg_lo:[1,0,0] neg_hi:[1,0,0]
	s_waitcnt lgkmcnt(11)
	v_pk_mul_f32 v[92:93], v[98:99], v[162:163]
	v_pk_mul_f32 v[94:95], v[98:99], v[160:161]
	v_pk_fma_f32 v[92:93], v[96:97], v[166:167], v[92:93]
	v_pk_fma_f32 v[94:95], v[96:97], v[164:165], v[94:95]
	v_add_f32_e32 v173, v92, v93
	v_add_f32_e32 v174, v94, v95
	ds_read2_b64 v[104:107], v168 offset0:96 offset1:112
	ds_read_b128 v[144:147], v244 offset:5632
	ds_read_b128 v[108:111], v244 offset:5888
	ds_read_b128 v[156:159], v244 offset:13824
	ds_read_b128 v[116:119], v244 offset:14080
	ds_read_b128 v[136:139], v244 offset:22016
	ds_read_b128 v[92:95], v244 offset:22272
	ds_read_b128 v[148:151], v244 offset:30208
	ds_read_b128 v[112:115], v244 offset:30464
	ds_read_b128 v[140:143], v244 offset:38400
	ds_read_b128 v[96:99], v244 offset:38656
	s_waitcnt lgkmcnt(14)
	v_pk_mul_f32 v[170:171], v[154:155], v[162:163]
	v_pk_mul_f32 v[154:155], v[154:155], v[160:161]
	v_pk_fma_f32 v[170:171], v[152:153], v[166:167], v[170:171]
	v_pk_fma_f32 v[152:153], v[152:153], v[164:165], v[154:155]
	v_add_f32_e32 v154, v170, v171
	v_cndmask_b32_e64 v170, v169, v172, s[6:7]
	v_cndmask_b32_e64 v171, v173, v174, s[6:7]
	v_cndmask_b32_e64 v169, v172, v169, s[6:7]
	v_cndmask_b32_e64 v172, v174, v173, s[6:7]
	v_add_f32_e32 v152, v152, v153
	v_add_f32_dpp v169, v170, v169 quad_perm:[1,0,3,2] row_mask:0xf bank_mask:0xf bound_ctrl:1
	v_add_f32_dpp v170, v171, v172 quad_perm:[1,0,3,2] row_mask:0xf bank_mask:0xf bound_ctrl:1
	v_add_f32_dpp v153, v154, v154 quad_perm:[1,0,3,2] row_mask:0xf bank_mask:0xf bound_ctrl:1
	v_add_f32_dpp v152, v152, v152 quad_perm:[1,0,3,2] row_mask:0xf bank_mask:0xf bound_ctrl:1
	v_cndmask_b32_e64 v171, v169, v170, s[8:9]
	v_cndmask_b32_e64 v169, v170, v169, s[8:9]
	v_add_f32_dpp v153, v153, v153 quad_perm:[2,3,0,1] row_mask:0xf bank_mask:0xf bound_ctrl:1
	v_add_f32_dpp v154, v152, v152 quad_perm:[2,3,0,1] row_mask:0xf bank_mask:0xf bound_ctrl:1
	v_add_f32_dpp v169, v171, v169 quad_perm:[2,3,0,1] row_mask:0xf bank_mask:0xf bound_ctrl:1
	v_add_f32_dpp v152, v153, v153 row_ror:4 row_mask:0xf bank_mask:0xf bound_ctrl:1
	v_add_f32_dpp v153, v154, v154 row_ror:4 row_mask:0xf bank_mask:0xf bound_ctrl:1
	v_mov_b32_e32 v154, 0
	v_mov_b32_e32 v155, 0
	v_add_f32_dpp v169, v169, v169 row_ror:4 row_mask:0xf bank_mask:0xf bound_ctrl:1
	v_mov_b32_e32 v170, 0
	v_mov_b32_dpp v154, v152 row_ror:8 row_mask:0xf bank_mask:0xf
	v_mov_b32_dpp v155, v153 row_ror:8 row_mask:0xf bank_mask:0xf
	v_mov_b32_dpp v170, v169 row_ror:8 row_mask:0xf bank_mask:0xf
	s_and_saveexec_b64 s[78:79], s[10:11]
	v_add_f32_e32 v169, v169, v170
	ds_write_b32 v245, v169 offset:2304
	s_or_b64 exec, exec, s[78:79]
	v_pk_mul_f32 v[166:167], v[128:129], v[166:167]
	v_pk_mul_f32 v[162:163], v[130:131], v[162:163]
	v_pk_mul_f32 v[128:129], v[128:129], v[164:165]
	v_pk_mul_f32 v[130:131], v[130:131], v[160:161]
	v_pk_fma_f32 v[166:167], v[132:133], v[80:81], v[166:167] op_sel_hi:[1,0,1]
	v_pk_fma_f32 v[162:163], v[134:135], v[80:81], v[162:163] op_sel_hi:[1,0,1]
	v_pk_fma_f32 v[128:129], v[132:133], v[80:81], v[128:129] op_sel:[0,1,0]
	v_pk_fma_f32 v[80:81], v[134:135], v[80:81], v[130:131] op_sel:[0,1,0]
	v_add_f32_e32 v130, v152, v154
	v_add_f32_e32 v132, v153, v155
	v_pk_fma_f32 v[134:135], v[120:121], v[130:131], v[166:167] op_sel_hi:[1,0,1] neg_lo:[1,0,0] neg_hi:[1,0,0]
	v_pk_fma_f32 v[130:131], v[122:123], v[130:131], v[162:163] op_sel_hi:[1,0,1] neg_lo:[1,0,0] neg_hi:[1,0,0]
	v_pk_fma_f32 v[80:81], v[122:123], v[132:133], v[80:81] op_sel_hi:[1,0,1] neg_lo:[1,0,0] neg_hi:[1,0,0]
	s_waitcnt lgkmcnt(12)
	v_pk_mul_f32 v[122:123], v[126:127], v[130:131]
	v_pk_fma_f32 v[120:121], v[120:121], v[132:133], v[128:129] op_sel_hi:[1,0,1] neg_lo:[1,0,0] neg_hi:[1,0,0]
	v_pk_fma_f32 v[122:123], v[124:125], v[134:135], v[122:123]
	v_pk_mul_f32 v[126:127], v[126:127], v[80:81]
	s_nop 0
	v_pk_fma_f32 v[124:125], v[124:125], v[120:121], v[126:127]
	v_add_f32_e32 v126, v122, v123
	v_pk_mul_f32 v[122:123], v[102:103], v[130:131]
	v_pk_mul_f32 v[102:103], v[102:103], v[80:81]
	v_pk_fma_f32 v[122:123], v[100:101], v[134:135], v[122:123]
	v_pk_fma_f32 v[100:101], v[100:101], v[120:121], v[102:103]
	v_add_f32_e32 v122, v122, v123
	v_add_f32_e32 v123, v100, v101
	v_pk_mul_f32 v[80:81], v[86:87], v[80:81]
	v_pk_mul_f32 v[102:103], v[86:87], v[130:131]
	v_pk_fma_f32 v[86:87], v[90:91], v[82:83], v[80:81] op_sel:[0,1,0]
	v_add_f32_dpp v80, v122, v122 quad_perm:[1,0,3,2] row_mask:0xf bank_mask:0xf bound_ctrl:1
	v_add_f32_dpp v81, v123, v123 quad_perm:[1,0,3,2] row_mask:0xf bank_mask:0xf bound_ctrl:1
	v_pk_mul_f32 v[100:101], v[84:85], v[134:135]
	v_add_f32_dpp v80, v80, v80 quad_perm:[2,3,0,1] row_mask:0xf bank_mask:0xf bound_ctrl:1
	v_add_f32_dpp v81, v81, v81 quad_perm:[2,3,0,1] row_mask:0xf bank_mask:0xf bound_ctrl:1
	v_pk_mul_f32 v[84:85], v[84:85], v[120:121]
	v_add_f32_dpp v80, v80, v80 row_ror:4 row_mask:0xf bank_mask:0xf bound_ctrl:1
	v_add_f32_dpp v81, v81, v81 row_ror:4 row_mask:0xf bank_mask:0xf bound_ctrl:1
	v_pk_fma_f32 v[100:101], v[88:89], v[82:83], v[100:101] op_sel_hi:[1,0,1]
	v_pk_fma_f32 v[102:103], v[90:91], v[82:83], v[102:103] op_sel_hi:[1,0,1]
	v_pk_fma_f32 v[88:89], v[88:89], v[82:83], v[84:85] op_sel:[0,1,0]
	v_add_f32_dpp v80, v80, v80 row_ror:8 row_mask:0xf bank_mask:0xf bound_ctrl:1
	v_add_f32_dpp v90, v81, v81 row_ror:8 row_mask:0xf bank_mask:0xf bound_ctrl:1
	v_pk_fma_f32 v[84:85], v[72:73], v[80:81], v[100:101] op_sel_hi:[1,0,1] neg_lo:[1,0,0] neg_hi:[1,0,0]
	v_pk_fma_f32 v[80:81], v[74:75], v[80:81], v[102:103] op_sel_hi:[1,0,1] neg_lo:[1,0,0] neg_hi:[1,0,0]
	v_pk_fma_f32 v[82:83], v[72:73], v[90:91], v[88:89] op_sel_hi:[1,0,1] neg_lo:[1,0,0] neg_hi:[1,0,0]
	v_pk_fma_f32 v[72:73], v[74:75], v[90:91], v[86:87] op_sel_hi:[1,0,1] neg_lo:[1,0,0] neg_hi:[1,0,0]
	s_waitcnt lgkmcnt(11)
	v_pk_mul_f32 v[74:75], v[78:79], v[80:81]
	v_pk_mul_f32 v[78:79], v[78:79], v[72:73]
	v_pk_fma_f32 v[74:75], v[76:77], v[84:85], v[74:75]
	v_pk_fma_f32 v[76:77], v[76:77], v[82:83], v[78:79]
	v_add_f32_e32 v78, v74, v75
	v_add_f32_e32 v79, v76, v77
	v_add_f32_e32 v124, v124, v125
	s_waitcnt lgkmcnt(7)
	v_pk_mul_f32 v[74:75], v[158:159], v[80:81]
	v_pk_mul_f32 v[76:77], v[158:159], v[72:73]
	v_pk_fma_f32 v[74:75], v[156:157], v[84:85], v[74:75]
	v_pk_fma_f32 v[76:77], v[156:157], v[82:83], v[76:77]
	v_cndmask_b32_e64 v86, v126, v124, s[6:7]
	v_cndmask_b32_e64 v87, v78, v79, s[6:7]
	v_cndmask_b32_e64 v88, v124, v126, s[6:7]
	v_cndmask_b32_e64 v78, v79, v78, s[6:7]
	v_add_f32_e32 v74, v74, v75
	v_add_f32_e32 v75, v76, v77
	v_add_f32_dpp v79, v86, v88 quad_perm:[1,0,3,2] row_mask:0xf bank_mask:0xf bound_ctrl:1
	v_add_f32_dpp v78, v87, v78 quad_perm:[1,0,3,2] row_mask:0xf bank_mask:0xf bound_ctrl:1
	v_add_f32_dpp v74, v74, v74 quad_perm:[1,0,3,2] row_mask:0xf bank_mask:0xf bound_ctrl:1
	v_add_f32_dpp v75, v75, v75 quad_perm:[1,0,3,2] row_mask:0xf bank_mask:0xf bound_ctrl:1
	v_cndmask_b32_e64 v86, v79, v78, s[8:9]
	v_cndmask_b32_e64 v78, v78, v79, s[8:9]
	v_add_f32_dpp v74, v74, v74 quad_perm:[2,3,0,1] row_mask:0xf bank_mask:0xf bound_ctrl:1
	v_add_f32_dpp v75, v75, v75 quad_perm:[2,3,0,1] row_mask:0xf bank_mask:0xf bound_ctrl:1
	v_add_f32_dpp v78, v86, v78 quad_perm:[2,3,0,1] row_mask:0xf bank_mask:0xf bound_ctrl:1
	v_add_f32_dpp v74, v74, v74 row_ror:4 row_mask:0xf bank_mask:0xf bound_ctrl:1
	v_add_f32_dpp v75, v75, v75 row_ror:4 row_mask:0xf bank_mask:0xf bound_ctrl:1
	v_mov_b32_e32 v76, 0
	v_mov_b32_e32 v77, 0
	v_add_f32_dpp v78, v78, v78 row_ror:4 row_mask:0xf bank_mask:0xf bound_ctrl:1
	v_mov_b32_e32 v79, 0
	v_mov_b32_dpp v76, v74 row_ror:8 row_mask:0xf bank_mask:0xf
	v_mov_b32_dpp v77, v75 row_ror:8 row_mask:0xf bank_mask:0xf
	v_mov_b32_dpp v79, v78 row_ror:8 row_mask:0xf bank_mask:0xf
	s_and_saveexec_b64 s[78:79], s[10:11]
	v_add_f32_e32 v78, v78, v79
	ds_write_b32 v245, v78 offset:2560
	s_or_b64 exec, exec, s[78:79]
	v_pk_mul_f32 v[78:79], v[144:145], v[84:85]
	v_pk_mul_f32 v[80:81], v[146:147], v[80:81]
	v_pk_mul_f32 v[72:73], v[146:147], v[72:73]
	s_waitcnt lgkmcnt(3)
	v_pk_fma_f32 v[78:79], v[148:149], v[104:105], v[78:79] op_sel_hi:[1,0,1]
	v_pk_fma_f32 v[80:81], v[150:151], v[104:105], v[80:81] op_sel_hi:[1,0,1]
	v_pk_mul_f32 v[82:83], v[144:145], v[82:83]
	v_pk_fma_f32 v[72:73], v[150:151], v[104:105], v[72:73] op_sel:[0,1,0]
	v_add_f32_e32 v74, v74, v76
	v_add_f32_e32 v76, v75, v77
	v_pk_fma_f32 v[82:83], v[148:149], v[104:105], v[82:83] op_sel:[0,1,0]
	v_pk_fma_f32 v[78:79], v[136:137], v[74:75], v[78:79] op_sel_hi:[1,0,1] neg_lo:[1,0,0] neg_hi:[1,0,0]
	v_pk_fma_f32 v[74:75], v[138:139], v[74:75], v[80:81] op_sel_hi:[1,0,1] neg_lo:[1,0,0] neg_hi:[1,0,0]
	v_pk_fma_f32 v[72:73], v[138:139], v[76:77], v[72:73] op_sel_hi:[1,0,1] neg_lo:[1,0,0] neg_hi:[1,0,0]
	v_pk_fma_f32 v[80:81], v[136:137], v[76:77], v[82:83] op_sel_hi:[1,0,1] neg_lo:[1,0,0] neg_hi:[1,0,0]
	s_waitcnt lgkmcnt(1)
	v_pk_mul_f32 v[76:77], v[142:143], v[74:75]
	v_pk_mul_f32 v[82:83], v[142:143], v[72:73]
	v_pk_fma_f32 v[76:77], v[140:141], v[78:79], v[76:77]
	v_pk_fma_f32 v[82:83], v[140:141], v[80:81], v[82:83]
	v_add_f32_e32 v84, v76, v77
	v_add_f32_e32 v85, v82, v83
	v_pk_mul_f32 v[76:77], v[118:119], v[74:75]
	v_pk_mul_f32 v[82:83], v[118:119], v[72:73]
	v_pk_fma_f32 v[76:77], v[116:117], v[78:79], v[76:77]
	v_pk_fma_f32 v[82:83], v[116:117], v[80:81], v[82:83]
	v_add_f32_e32 v86, v76, v77
	v_add_f32_e32 v82, v82, v83
	v_pk_mul_f32 v[76:77], v[108:109], v[78:79]
	v_pk_mul_f32 v[78:79], v[108:109], v[80:81]
	v_add_f32_dpp v80, v86, v86 quad_perm:[1,0,3,2] row_mask:0xf bank_mask:0xf bound_ctrl:1
	v_add_f32_dpp v81, v82, v82 quad_perm:[1,0,3,2] row_mask:0xf bank_mask:0xf bound_ctrl:1
	v_pk_mul_f32 v[74:75], v[110:111], v[74:75]
	v_add_f32_dpp v80, v80, v80 quad_perm:[2,3,0,1] row_mask:0xf bank_mask:0xf bound_ctrl:1
	v_add_f32_dpp v81, v81, v81 quad_perm:[2,3,0,1] row_mask:0xf bank_mask:0xf bound_ctrl:1
	v_pk_mul_f32 v[72:73], v[110:111], v[72:73]
	v_add_f32_dpp v80, v80, v80 row_ror:4 row_mask:0xf bank_mask:0xf bound_ctrl:1
	v_add_f32_dpp v81, v81, v81 row_ror:4 row_mask:0xf bank_mask:0xf bound_ctrl:1
	v_pk_fma_f32 v[74:75], v[114:115], v[106:107], v[74:75] op_sel_hi:[1,0,1]
	v_pk_fma_f32 v[72:73], v[114:115], v[106:107], v[72:73] op_sel:[0,1,0]
	v_add_f32_dpp v80, v80, v80 row_ror:8 row_mask:0xf bank_mask:0xf bound_ctrl:1
	v_add_f32_dpp v82, v81, v81 row_ror:8 row_mask:0xf bank_mask:0xf bound_ctrl:1
	v_pk_fma_f32 v[76:77], v[112:113], v[106:107], v[76:77] op_sel_hi:[1,0,1]
	v_pk_fma_f32 v[78:79], v[112:113], v[106:107], v[78:79] op_sel:[0,1,0]
	v_pk_fma_f32 v[90:91], v[94:95], v[80:81], v[74:75] op_sel_hi:[1,0,1] neg_lo:[1,0,0] neg_hi:[1,0,0]
	v_pk_fma_f32 v[94:95], v[94:95], v[82:83], v[72:73] op_sel_hi:[1,0,1] neg_lo:[1,0,0] neg_hi:[1,0,0]
	v_pk_fma_f32 v[88:89], v[92:93], v[80:81], v[76:77] op_sel_hi:[1,0,1] neg_lo:[1,0,0] neg_hi:[1,0,0]
	v_pk_fma_f32 v[92:93], v[92:93], v[82:83], v[78:79] op_sel_hi:[1,0,1] neg_lo:[1,0,0] neg_hi:[1,0,0]
	s_waitcnt lgkmcnt(0)
	v_pk_mul_f32 v[72:73], v[98:99], v[90:91]
	v_pk_mul_f32 v[74:75], v[98:99], v[94:95]
	v_pk_fma_f32 v[72:73], v[96:97], v[88:89], v[72:73]
	v_pk_fma_f32 v[74:75], v[96:97], v[92:93], v[74:75]
	v_add_f32_e32 v72, v72, v73
	v_add_f32_e32 v73, v74, v75
	v_cndmask_b32_e64 v74, v84, v85, s[6:7]
	v_cndmask_b32_e64 v75, v72, v73, s[6:7]
	v_cndmask_b32_e64 v76, v85, v84, s[6:7]
	v_cndmask_b32_e64 v72, v73, v72, s[6:7]
	s_nop 0
	v_add_f32_dpp v73, v74, v76 quad_perm:[1,0,3,2] row_mask:0xf bank_mask:0xf bound_ctrl:1
	v_add_f32_dpp v72, v75, v72 quad_perm:[1,0,3,2] row_mask:0xf bank_mask:0xf bound_ctrl:1
	v_cndmask_b32_e64 v74, v73, v72, s[8:9]
	v_cndmask_b32_e64 v72, v72, v73, s[8:9]
	v_mov_b32_e32 v73, 0
	s_nop 0
	v_add_f32_dpp v72, v74, v72 quad_perm:[2,3,0,1] row_mask:0xf bank_mask:0xf bound_ctrl:1
	s_nop 1
	v_add_f32_dpp v72, v72, v72 row_ror:4 row_mask:0xf bank_mask:0xf bound_ctrl:1
	s_nop 1
	v_mov_b32_dpp v73, v72 row_ror:8 row_mask:0xf bank_mask:0xf
	s_and_saveexec_b64 s[78:79], s[10:11]
	v_add3_u32 v74, v176, v239, v197
	v_add_f32_e32 v72, v72, v73
	ds_write_b32 v74, v72 offset:2816
	s_or_b64 exec, exec, s[78:79]
	s_ashr_i32 s28, s24, 5
	s_add_i32 s29, s24, 0xffffff00
	s_not_b32 s28, s28
	s_lshr_b32 s29, s29, 5
	s_cmpk_lt_i32 s24, 0x100
	s_cselect_b32 s28, s28, s29
	s_ashr_i32 s29, s28, 31
	s_lshl_b32 s24, s24, 5
	s_lshl_b64 s[28:29], s[28:29], 10
	s_and_b32 s24, s24, 0x3e0
	s_or_b32 s24, s28, s24
	v_mov_b32_e32 v73, s29
	v_or_b32_e32 v72, s24, v192
	v_lshlrev_b64 v[72:73], 8, v[72:73]
	v_lshl_add_u64 v[72:73], v[198:199], 0, v[72:73]
	global_store_dwordx4 v[72:73], v[88:91], off
	global_store_dwordx4 v[72:73], v[92:95], off offset:256
	s_mul_i32 s24, s94, 3
	s_add_i32 s24, s70, s24
	s_cmpk_gt_i32 s24, 0x10ff
	s_cbranch_scc1 .LBB0_346
.LBB0_337:
	ds_read2_b64 v[72:75], v168 offset0:128 offset1:144
	ds_read_b128 v[76:79], v244 offset:39168
	ds_read_b128 v[80:83], v244 offset:38912
	ds_read_b128 v[88:91], v244 offset:30976
	ds_read_b128 v[112:115], v244 offset:30720
	ds_read_b128 v[116:119], v244 offset:22784
	ds_read_b128 v[120:123], v244 offset:22528
	ds_read_b128 v[124:127], v244 offset:14592
	ds_read_b128 v[144:147], v244 offset:14336
	ds_read_b128 v[148:151], v244 offset:6400
	ds_read_b128 v[152:155], v244 offset:6144
	ds_read2_b64 v[96:99], v168 offset0:160 offset1:176
	ds_read_b128 v[136:139], v244 offset:6656
	ds_read_b128 v[100:103], v244 offset:6912
	ds_read_b128 v[156:159], v244 offset:14848
	ds_read_b128 v[108:111], v244 offset:15104
	ds_read_b128 v[128:131], v244 offset:23040
	ds_read_b128 v[84:87], v244 offset:23296
	ds_read_b128 v[140:143], v244 offset:31232
	ds_read_b128 v[104:107], v244 offset:31488
	ds_read_b128 v[132:135], v244 offset:39424
	ds_read_b128 v[92:95], v244 offset:39680
	s_waitcnt lgkmcnt(13)
	v_pk_mul_f32 v[160:161], v[66:67], v[146:147]
	v_pk_mul_f32 v[146:147], v[70:71], v[146:147]
	v_pk_fma_f32 v[160:161], v[64:65], v[144:145], v[160:161]
	v_pk_fma_f32 v[144:145], v[68:69], v[144:145], v[146:147]
	v_add_f32_e32 v146, v160, v161
	v_add_f32_e32 v144, v144, v145
	s_waitcnt lgkmcnt(11)
	v_pk_mul_f32 v[68:69], v[68:69], v[152:153]
	v_add_f32_dpp v145, v146, v146 quad_perm:[1,0,3,2] row_mask:0xf bank_mask:0xf bound_ctrl:1
	v_add_f32_dpp v144, v144, v144 quad_perm:[1,0,3,2] row_mask:0xf bank_mask:0xf bound_ctrl:1
	v_pk_mul_f32 v[64:65], v[64:65], v[152:153]
	v_add_f32_dpp v145, v145, v145 quad_perm:[2,3,0,1] row_mask:0xf bank_mask:0xf bound_ctrl:1
	v_add_f32_dpp v144, v144, v144 quad_perm:[2,3,0,1] row_mask:0xf bank_mask:0xf bound_ctrl:1
	v_pk_mul_f32 v[66:67], v[66:67], v[154:155]
	v_add_f32_dpp v146, v145, v145 row_ror:4 row_mask:0xf bank_mask:0xf bound_ctrl:1
	v_add_f32_dpp v144, v144, v144 row_ror:4 row_mask:0xf bank_mask:0xf bound_ctrl:1
	v_pk_fma_f32 v[68:69], v[72:73], v[112:113], v[68:69] op_sel:[1,0,0]
	v_pk_mul_f32 v[70:71], v[70:71], v[154:155]
	v_pk_fma_f32 v[64:65], v[72:73], v[112:113], v[64:65] op_sel_hi:[0,1,1]
	v_add_f32_dpp v112, v146, v146 row_ror:8 row_mask:0xf bank_mask:0xf bound_ctrl:1
	v_pk_fma_f32 v[66:67], v[72:73], v[114:115], v[66:67] op_sel_hi:[0,1,1]
	v_add_f32_dpp v144, v144, v144 row_ror:8 row_mask:0xf bank_mask:0xf bound_ctrl:1
	v_pk_fma_f32 v[70:71], v[72:73], v[114:115], v[70:71] op_sel:[1,0,0]
	v_pk_fma_f32 v[66:67], v[122:123], v[112:113], v[66:67] op_sel_hi:[1,0,1] neg_lo:[1,0,0] neg_hi:[1,0,0]
	v_pk_fma_f32 v[70:71], v[122:123], v[144:145], v[70:71] op_sel_hi:[1,0,1] neg_lo:[1,0,0] neg_hi:[1,0,0]
	v_pk_fma_f32 v[64:65], v[120:121], v[112:113], v[64:65] op_sel_hi:[1,0,1] neg_lo:[1,0,0] neg_hi:[1,0,0]
	v_pk_mul_f32 v[72:73], v[82:83], v[66:67]
	v_pk_fma_f32 v[68:69], v[120:121], v[144:145], v[68:69] op_sel_hi:[1,0,1] neg_lo:[1,0,0] neg_hi:[1,0,0]
	v_pk_mul_f32 v[144:145], v[82:83], v[70:71]
	v_pk_fma_f32 v[72:73], v[80:81], v[64:65], v[72:73]
	v_pk_fma_f32 v[144:145], v[80:81], v[68:69], v[144:145]
	v_add_f32_e32 v163, v72, v73
	v_pk_mul_f32 v[72:73], v[126:127], v[66:67]
	v_pk_mul_f32 v[80:81], v[126:127], v[70:71]
	v_pk_fma_f32 v[72:73], v[124:125], v[64:65], v[72:73]
	v_pk_fma_f32 v[80:81], v[124:125], v[68:69], v[80:81]
	v_add_f32_e32 v72, v72, v73
	v_add_f32_e32 v73, v80, v81
	v_pk_mul_f32 v[64:65], v[148:149], v[64:65]
	v_add_f32_dpp v72, v72, v72 quad_perm:[1,0,3,2] row_mask:0xf bank_mask:0xf bound_ctrl:1
	v_add_f32_dpp v73, v73, v73 quad_perm:[1,0,3,2] row_mask:0xf bank_mask:0xf bound_ctrl:1
	v_pk_mul_f32 v[66:67], v[150:151], v[66:67]
	v_add_f32_dpp v72, v72, v72 quad_perm:[2,3,0,1] row_mask:0xf bank_mask:0xf bound_ctrl:1
	v_add_f32_dpp v73, v73, v73 quad_perm:[2,3,0,1] row_mask:0xf bank_mask:0xf bound_ctrl:1
	v_pk_mul_f32 v[68:69], v[148:149], v[68:69]
	v_pk_mul_f32 v[70:71], v[150:151], v[70:71]
	v_add_f32_dpp v72, v72, v72 row_ror:4 row_mask:0xf bank_mask:0xf bound_ctrl:1
	v_add_f32_dpp v73, v73, v73 row_ror:4 row_mask:0xf bank_mask:0xf bound_ctrl:1
	v_pk_fma_f32 v[64:65], v[74:75], v[88:89], v[64:65] op_sel_hi:[0,1,1]
	v_pk_fma_f32 v[66:67], v[74:75], v[90:91], v[66:67] op_sel_hi:[0,1,1]
	v_pk_fma_f32 v[68:69], v[74:75], v[88:89], v[68:69] op_sel:[1,0,0]
	v_pk_fma_f32 v[70:71], v[74:75], v[90:91], v[70:71] op_sel:[1,0,0]
	v_add_f32_dpp v72, v72, v72 row_ror:8 row_mask:0xf bank_mask:0xf bound_ctrl:1
	v_add_f32_dpp v74, v73, v73 row_ror:8 row_mask:0xf bank_mask:0xf bound_ctrl:1
	v_pk_fma_f32 v[150:151], v[118:119], v[72:73], v[66:67] op_sel_hi:[1,0,1] neg_lo:[1,0,0] neg_hi:[1,0,0]
	v_pk_fma_f32 v[148:149], v[118:119], v[74:75], v[70:71] op_sel_hi:[1,0,1] neg_lo:[1,0,0] neg_hi:[1,0,0]
	v_pk_fma_f32 v[154:155], v[116:117], v[72:73], v[64:65] op_sel_hi:[1,0,1] neg_lo:[1,0,0] neg_hi:[1,0,0]
	v_pk_fma_f32 v[152:153], v[116:117], v[74:75], v[68:69] op_sel_hi:[1,0,1] neg_lo:[1,0,0] neg_hi:[1,0,0]
	v_pk_mul_f32 v[64:65], v[78:79], v[150:151]
	v_pk_mul_f32 v[66:67], v[78:79], v[148:149]
	v_pk_fma_f32 v[64:65], v[76:77], v[154:155], v[64:65]
	v_pk_fma_f32 v[66:67], v[76:77], v[152:153], v[66:67]
	v_add_f32_e32 v162, v144, v145
	v_add_f32_e32 v164, v64, v65
	v_add_f32_e32 v165, v66, v67
	ds_read2_b64 v[72:75], v168 offset0:192 offset1:208
	ds_read_b128 v[120:123], v244 offset:7168
	ds_read_b128 v[76:79], v244 offset:7424
	ds_read_b128 v[144:147], v244 offset:15360
	ds_read_b128 v[88:91], v244 offset:15616
	ds_read_b128 v[112:115], v244 offset:23552
	ds_read_b128 v[64:67], v244 offset:23808
	ds_read_b128 v[124:127], v244 offset:31744
	ds_read_b128 v[80:83], v244 offset:32000
	ds_read_b128 v[116:119], v244 offset:39936
	ds_read_b128 v[68:71], v244 offset:40192
	s_waitcnt lgkmcnt(14)
	v_pk_mul_f32 v[160:161], v[158:159], v[150:151]
	v_pk_mul_f32 v[158:159], v[158:159], v[148:149]
	v_pk_fma_f32 v[160:161], v[156:157], v[154:155], v[160:161]
	v_pk_fma_f32 v[156:157], v[156:157], v[152:153], v[158:159]
	v_add_f32_e32 v158, v160, v161
	v_cndmask_b32_e64 v160, v163, v162, s[6:7]
	v_cndmask_b32_e64 v161, v164, v165, s[6:7]
	v_cndmask_b32_e64 v162, v162, v163, s[6:7]
	v_cndmask_b32_e64 v163, v165, v164, s[6:7]
	v_add_f32_e32 v156, v156, v157
	v_add_f32_dpp v160, v160, v162 quad_perm:[1,0,3,2] row_mask:0xf bank_mask:0xf bound_ctrl:1
	v_add_f32_dpp v161, v161, v163 quad_perm:[1,0,3,2] row_mask:0xf bank_mask:0xf bound_ctrl:1
	v_add_f32_dpp v157, v158, v158 quad_perm:[1,0,3,2] row_mask:0xf bank_mask:0xf bound_ctrl:1
	v_add_f32_dpp v156, v156, v156 quad_perm:[1,0,3,2] row_mask:0xf bank_mask:0xf bound_ctrl:1
	v_cndmask_b32_e64 v162, v160, v161, s[8:9]
	v_cndmask_b32_e64 v160, v161, v160, s[8:9]
	v_add_f32_dpp v157, v157, v157 quad_perm:[2,3,0,1] row_mask:0xf bank_mask:0xf bound_ctrl:1
	v_add_f32_dpp v158, v156, v156 quad_perm:[2,3,0,1] row_mask:0xf bank_mask:0xf bound_ctrl:1
	v_add_f32_dpp v160, v162, v160 quad_perm:[2,3,0,1] row_mask:0xf bank_mask:0xf bound_ctrl:1
	v_add_f32_dpp v156, v157, v157 row_ror:4 row_mask:0xf bank_mask:0xf bound_ctrl:1
	v_add_f32_dpp v157, v158, v158 row_ror:4 row_mask:0xf bank_mask:0xf bound_ctrl:1
	v_mov_b32_e32 v158, v177
	v_mov_b32_e32 v159, v177
	v_add_f32_dpp v160, v160, v160 row_ror:4 row_mask:0xf bank_mask:0xf bound_ctrl:1
	v_mov_b32_e32 v161, v177
	v_mov_b32_dpp v158, v156 row_ror:8 row_mask:0xf bank_mask:0xf
	v_mov_b32_dpp v159, v157 row_ror:8 row_mask:0xf bank_mask:0xf
	v_mov_b32_dpp v161, v160 row_ror:8 row_mask:0xf bank_mask:0xf
	s_and_saveexec_b64 s[78:79], s[10:11]
	v_add_f32_e32 v160, v160, v161
	ds_write_b32 v245, v160 offset:3072
	s_or_b64 exec, exec, s[78:79]
	v_pk_mul_f32 v[154:155], v[136:137], v[154:155]
	v_pk_mul_f32 v[150:151], v[138:139], v[150:151]
	v_pk_mul_f32 v[136:137], v[136:137], v[152:153]
	v_pk_mul_f32 v[138:139], v[138:139], v[148:149]
	v_pk_fma_f32 v[154:155], v[140:141], v[96:97], v[154:155] op_sel_hi:[1,0,1]
	v_pk_fma_f32 v[150:151], v[142:143], v[96:97], v[150:151] op_sel_hi:[1,0,1]
	v_pk_fma_f32 v[136:137], v[140:141], v[96:97], v[136:137] op_sel:[0,1,0]
	v_pk_fma_f32 v[96:97], v[142:143], v[96:97], v[138:139] op_sel:[0,1,0]
	v_add_f32_e32 v138, v156, v158
	v_add_f32_e32 v140, v157, v159
	v_pk_fma_f32 v[142:143], v[128:129], v[138:139], v[154:155] op_sel_hi:[1,0,1] neg_lo:[1,0,0] neg_hi:[1,0,0]
	v_pk_fma_f32 v[138:139], v[130:131], v[138:139], v[150:151] op_sel_hi:[1,0,1] neg_lo:[1,0,0] neg_hi:[1,0,0]
	v_pk_fma_f32 v[96:97], v[130:131], v[140:141], v[96:97] op_sel_hi:[1,0,1] neg_lo:[1,0,0] neg_hi:[1,0,0]
	s_waitcnt lgkmcnt(12)
	v_pk_mul_f32 v[130:131], v[134:135], v[138:139]
	v_pk_fma_f32 v[128:129], v[128:129], v[140:141], v[136:137] op_sel_hi:[1,0,1] neg_lo:[1,0,0] neg_hi:[1,0,0]
	v_pk_fma_f32 v[130:131], v[132:133], v[142:143], v[130:131]
	v_pk_mul_f32 v[134:135], v[134:135], v[96:97]
	v_add_f32_e32 v162, v130, v131
	v_pk_mul_f32 v[130:131], v[110:111], v[138:139]
	v_pk_mul_f32 v[110:111], v[110:111], v[96:97]
	v_pk_fma_f32 v[130:131], v[108:109], v[142:143], v[130:131]
	v_pk_fma_f32 v[108:109], v[108:109], v[128:129], v[110:111]
	v_add_f32_e32 v130, v130, v131
	v_add_f32_e32 v131, v108, v109
	v_pk_mul_f32 v[108:109], v[100:101], v[142:143]
	v_pk_mul_f32 v[110:111], v[102:103], v[138:139]
	v_pk_mul_f32 v[100:101], v[100:101], v[128:129]
	v_pk_mul_f32 v[96:97], v[102:103], v[96:97]
	v_pk_fma_f32 v[108:109], v[104:105], v[98:99], v[108:109] op_sel_hi:[1,0,1]
	v_pk_fma_f32 v[110:111], v[106:107], v[98:99], v[110:111] op_sel_hi:[1,0,1]
	v_pk_fma_f32 v[100:101], v[104:105], v[98:99], v[100:101] op_sel:[0,1,0]
	v_pk_fma_f32 v[96:97], v[106:107], v[98:99], v[96:97] op_sel:[0,1,0]
	v_add_f32_dpp v98, v130, v130 quad_perm:[1,0,3,2] row_mask:0xf bank_mask:0xf bound_ctrl:1
	v_add_f32_dpp v99, v131, v131 quad_perm:[1,0,3,2] row_mask:0xf bank_mask:0xf bound_ctrl:1
	v_pk_fma_f32 v[132:133], v[132:133], v[128:129], v[134:135]
	v_add_f32_dpp v98, v98, v98 quad_perm:[2,3,0,1] row_mask:0xf bank_mask:0xf bound_ctrl:1
	v_add_f32_dpp v99, v99, v99 quad_perm:[2,3,0,1] row_mask:0xf bank_mask:0xf bound_ctrl:1
	v_add_f32_e32 v163, v132, v133
	v_add_f32_dpp v98, v98, v98 row_ror:4 row_mask:0xf bank_mask:0xf bound_ctrl:1
	v_add_f32_dpp v99, v99, v99 row_ror:4 row_mask:0xf bank_mask:0xf bound_ctrl:1
	s_nop 0
	v_add_f32_dpp v98, v98, v98 row_ror:8 row_mask:0xf bank_mask:0xf bound_ctrl:1
	v_add_f32_dpp v102, v99, v99 row_ror:8 row_mask:0xf bank_mask:0xf bound_ctrl:1
	v_pk_fma_f32 v[154:155], v[86:87], v[98:99], v[110:111] op_sel_hi:[1,0,1] neg_lo:[1,0,0] neg_hi:[1,0,0]
	v_pk_fma_f32 v[152:153], v[86:87], v[102:103], v[96:97] op_sel_hi:[1,0,1] neg_lo:[1,0,0] neg_hi:[1,0,0]
	v_pk_fma_f32 v[158:159], v[84:85], v[98:99], v[108:109] op_sel_hi:[1,0,1] neg_lo:[1,0,0] neg_hi:[1,0,0]
	v_pk_fma_f32 v[156:157], v[84:85], v[102:103], v[100:101] op_sel_hi:[1,0,1] neg_lo:[1,0,0] neg_hi:[1,0,0]
	s_waitcnt lgkmcnt(11)
	v_pk_mul_f32 v[84:85], v[94:95], v[154:155]
	v_pk_mul_f32 v[86:87], v[94:95], v[152:153]
	v_pk_fma_f32 v[84:85], v[92:93], v[158:159], v[84:85]
	v_pk_fma_f32 v[86:87], v[92:93], v[156:157], v[86:87]
	v_add_f32_e32 v164, v84, v85
	v_add_f32_e32 v165, v86, v87
	ds_read2_b64 v[92:95], v168 offset0:224 offset1:240
	ds_read_b128 v[136:139], v244 offset:7680
	ds_read_b128 v[100:103], v244 offset:7936
	ds_read_b128 v[148:151], v244 offset:15872
	ds_read_b128 v[108:111], v244 offset:16128
	ds_read_b128 v[128:131], v244 offset:24064
	ds_read_b128 v[84:87], v244 offset:24320
	ds_read_b128 v[140:143], v244 offset:32256
	ds_read_b128 v[104:107], v244 offset:32512
	ds_read_b128 v[132:135], v244 offset:40448
	ds_read_b128 v[96:99], v244 offset:40704
	s_waitcnt lgkmcnt(14)
	v_pk_mul_f32 v[160:161], v[146:147], v[154:155]
	v_pk_mul_f32 v[146:147], v[146:147], v[152:153]
	v_pk_fma_f32 v[160:161], v[144:145], v[158:159], v[160:161]
	v_pk_fma_f32 v[144:145], v[144:145], v[156:157], v[146:147]
	v_add_f32_e32 v146, v160, v161
	v_cndmask_b32_e64 v160, v162, v163, s[6:7]
	v_cndmask_b32_e64 v161, v164, v165, s[6:7]
	v_cndmask_b32_e64 v162, v163, v162, s[6:7]
	v_cndmask_b32_e64 v163, v165, v164, s[6:7]
	v_add_f32_e32 v144, v144, v145
	v_add_f32_dpp v160, v160, v162 quad_perm:[1,0,3,2] row_mask:0xf bank_mask:0xf bound_ctrl:1
	v_add_f32_dpp v161, v161, v163 quad_perm:[1,0,3,2] row_mask:0xf bank_mask:0xf bound_ctrl:1
	v_add_f32_dpp v145, v146, v146 quad_perm:[1,0,3,2] row_mask:0xf bank_mask:0xf bound_ctrl:1
	v_add_f32_dpp v144, v144, v144 quad_perm:[1,0,3,2] row_mask:0xf bank_mask:0xf bound_ctrl:1
	v_cndmask_b32_e64 v162, v160, v161, s[8:9]
	v_cndmask_b32_e64 v160, v161, v160, s[8:9]
	v_add_f32_dpp v145, v145, v145 quad_perm:[2,3,0,1] row_mask:0xf bank_mask:0xf bound_ctrl:1
	v_add_f32_dpp v146, v144, v144 quad_perm:[2,3,0,1] row_mask:0xf bank_mask:0xf bound_ctrl:1
	v_add_f32_dpp v160, v162, v160 quad_perm:[2,3,0,1] row_mask:0xf bank_mask:0xf bound_ctrl:1
	v_add_f32_dpp v144, v145, v145 row_ror:4 row_mask:0xf bank_mask:0xf bound_ctrl:1
	v_add_f32_dpp v145, v146, v146 row_ror:4 row_mask:0xf bank_mask:0xf bound_ctrl:1
	v_mov_b32_e32 v146, 0
	v_mov_b32_e32 v147, 0
	v_add_f32_dpp v160, v160, v160 row_ror:4 row_mask:0xf bank_mask:0xf bound_ctrl:1
	v_mov_b32_e32 v161, 0
	v_mov_b32_dpp v146, v144 row_ror:8 row_mask:0xf bank_mask:0xf
	v_mov_b32_dpp v147, v145 row_ror:8 row_mask:0xf bank_mask:0xf
	v_mov_b32_dpp v161, v160 row_ror:8 row_mask:0xf bank_mask:0xf
	s_and_saveexec_b64 s[78:79], s[10:11]
	v_add_f32_e32 v160, v160, v161
	ds_write_b32 v245, v160 offset:3328
	s_or_b64 exec, exec, s[78:79]
	v_pk_mul_f32 v[158:159], v[120:121], v[158:159]
	v_pk_mul_f32 v[154:155], v[122:123], v[154:155]
	v_pk_mul_f32 v[120:121], v[120:121], v[156:157]
	v_pk_mul_f32 v[122:123], v[122:123], v[152:153]
	v_pk_fma_f32 v[158:159], v[124:125], v[72:73], v[158:159] op_sel_hi:[1,0,1]
	v_pk_fma_f32 v[154:155], v[126:127], v[72:73], v[154:155] op_sel_hi:[1,0,1]
	v_pk_fma_f32 v[120:121], v[124:125], v[72:73], v[120:121] op_sel:[0,1,0]
	v_pk_fma_f32 v[72:73], v[126:127], v[72:73], v[122:123] op_sel:[0,1,0]
	v_add_f32_e32 v122, v144, v146
	v_add_f32_e32 v124, v145, v147
	v_pk_fma_f32 v[126:127], v[112:113], v[122:123], v[158:159] op_sel_hi:[1,0,1] neg_lo:[1,0,0] neg_hi:[1,0,0]
	v_pk_fma_f32 v[122:123], v[114:115], v[122:123], v[154:155] op_sel_hi:[1,0,1] neg_lo:[1,0,0] neg_hi:[1,0,0]
	v_pk_fma_f32 v[72:73], v[114:115], v[124:125], v[72:73] op_sel_hi:[1,0,1] neg_lo:[1,0,0] neg_hi:[1,0,0]
	s_waitcnt lgkmcnt(12)
	v_pk_mul_f32 v[114:115], v[118:119], v[122:123]
	v_pk_fma_f32 v[112:113], v[112:113], v[124:125], v[120:121] op_sel_hi:[1,0,1] neg_lo:[1,0,0] neg_hi:[1,0,0]
	v_pk_fma_f32 v[114:115], v[116:117], v[126:127], v[114:115]
	v_pk_mul_f32 v[118:119], v[118:119], v[72:73]
	s_nop 0
	v_pk_fma_f32 v[116:117], v[116:117], v[112:113], v[118:119]
	v_add_f32_e32 v118, v114, v115
	v_pk_mul_f32 v[114:115], v[90:91], v[122:123]
	v_pk_mul_f32 v[90:91], v[90:91], v[72:73]
	v_pk_fma_f32 v[114:115], v[88:89], v[126:127], v[114:115]
	v_pk_fma_f32 v[88:89], v[88:89], v[112:113], v[90:91]
	v_add_f32_e32 v114, v114, v115
	v_add_f32_e32 v115, v88, v89
	v_pk_mul_f32 v[72:73], v[78:79], v[72:73]
	v_pk_mul_f32 v[90:91], v[78:79], v[122:123]
	v_pk_fma_f32 v[78:79], v[82:83], v[74:75], v[72:73] op_sel:[0,1,0]
	v_add_f32_dpp v72, v114, v114 quad_perm:[1,0,3,2] row_mask:0xf bank_mask:0xf bound_ctrl:1
	v_add_f32_dpp v73, v115, v115 quad_perm:[1,0,3,2] row_mask:0xf bank_mask:0xf bound_ctrl:1
	v_pk_mul_f32 v[88:89], v[76:77], v[126:127]
	v_add_f32_dpp v72, v72, v72 quad_perm:[2,3,0,1] row_mask:0xf bank_mask:0xf bound_ctrl:1
	v_add_f32_dpp v73, v73, v73 quad_perm:[2,3,0,1] row_mask:0xf bank_mask:0xf bound_ctrl:1
	v_pk_mul_f32 v[76:77], v[76:77], v[112:113]
	v_add_f32_dpp v72, v72, v72 row_ror:4 row_mask:0xf bank_mask:0xf bound_ctrl:1
	v_add_f32_dpp v73, v73, v73 row_ror:4 row_mask:0xf bank_mask:0xf bound_ctrl:1
	v_pk_fma_f32 v[88:89], v[80:81], v[74:75], v[88:89] op_sel_hi:[1,0,1]
	v_pk_fma_f32 v[90:91], v[82:83], v[74:75], v[90:91] op_sel_hi:[1,0,1]
	v_pk_fma_f32 v[80:81], v[80:81], v[74:75], v[76:77] op_sel:[0,1,0]
	v_add_f32_dpp v72, v72, v72 row_ror:8 row_mask:0xf bank_mask:0xf bound_ctrl:1
	v_add_f32_dpp v82, v73, v73 row_ror:8 row_mask:0xf bank_mask:0xf bound_ctrl:1
	v_pk_fma_f32 v[76:77], v[64:65], v[72:73], v[88:89] op_sel_hi:[1,0,1] neg_lo:[1,0,0] neg_hi:[1,0,0]
	v_pk_fma_f32 v[72:73], v[66:67], v[72:73], v[90:91] op_sel_hi:[1,0,1] neg_lo:[1,0,0] neg_hi:[1,0,0]
	v_pk_fma_f32 v[74:75], v[64:65], v[82:83], v[80:81] op_sel_hi:[1,0,1] neg_lo:[1,0,0] neg_hi:[1,0,0]
	v_pk_fma_f32 v[64:65], v[66:67], v[82:83], v[78:79] op_sel_hi:[1,0,1] neg_lo:[1,0,0] neg_hi:[1,0,0]
	s_waitcnt lgkmcnt(11)
	v_pk_mul_f32 v[66:67], v[70:71], v[72:73]
	v_pk_mul_f32 v[70:71], v[70:71], v[64:65]
	v_pk_fma_f32 v[66:67], v[68:69], v[76:77], v[66:67]
	v_pk_fma_f32 v[68:69], v[68:69], v[74:75], v[70:71]
	v_add_f32_e32 v70, v66, v67
	v_add_f32_e32 v71, v68, v69
	v_add_f32_e32 v116, v116, v117
	s_waitcnt lgkmcnt(7)
	v_pk_mul_f32 v[66:67], v[150:151], v[72:73]
	v_pk_mul_f32 v[68:69], v[150:151], v[64:65]
	v_pk_fma_f32 v[66:67], v[148:149], v[76:77], v[66:67]
	v_pk_fma_f32 v[68:69], v[148:149], v[74:75], v[68:69]
	v_cndmask_b32_e64 v78, v118, v116, s[6:7]
	v_cndmask_b32_e64 v79, v70, v71, s[6:7]
	v_cndmask_b32_e64 v80, v116, v118, s[6:7]
	v_cndmask_b32_e64 v70, v71, v70, s[6:7]
	v_add_f32_e32 v66, v66, v67
	v_add_f32_e32 v67, v68, v69
	v_add_f32_dpp v71, v78, v80 quad_perm:[1,0,3,2] row_mask:0xf bank_mask:0xf bound_ctrl:1
	v_add_f32_dpp v70, v79, v70 quad_perm:[1,0,3,2] row_mask:0xf bank_mask:0xf bound_ctrl:1
	v_add_f32_dpp v66, v66, v66 quad_perm:[1,0,3,2] row_mask:0xf bank_mask:0xf bound_ctrl:1
	v_add_f32_dpp v67, v67, v67 quad_perm:[1,0,3,2] row_mask:0xf bank_mask:0xf bound_ctrl:1
	v_cndmask_b32_e64 v78, v71, v70, s[8:9]
	v_cndmask_b32_e64 v70, v70, v71, s[8:9]
	v_add_f32_dpp v66, v66, v66 quad_perm:[2,3,0,1] row_mask:0xf bank_mask:0xf bound_ctrl:1
	v_add_f32_dpp v67, v67, v67 quad_perm:[2,3,0,1] row_mask:0xf bank_mask:0xf bound_ctrl:1
	v_add_f32_dpp v70, v78, v70 quad_perm:[2,3,0,1] row_mask:0xf bank_mask:0xf bound_ctrl:1
	v_add_f32_dpp v66, v66, v66 row_ror:4 row_mask:0xf bank_mask:0xf bound_ctrl:1
	v_add_f32_dpp v67, v67, v67 row_ror:4 row_mask:0xf bank_mask:0xf bound_ctrl:1
	v_mov_b32_e32 v68, 0
	v_mov_b32_e32 v69, 0
	v_add_f32_dpp v70, v70, v70 row_ror:4 row_mask:0xf bank_mask:0xf bound_ctrl:1
	v_mov_b32_e32 v71, 0
	v_mov_b32_dpp v68, v66 row_ror:8 row_mask:0xf bank_mask:0xf
	v_mov_b32_dpp v69, v67 row_ror:8 row_mask:0xf bank_mask:0xf
	v_mov_b32_dpp v71, v70 row_ror:8 row_mask:0xf bank_mask:0xf
	s_and_saveexec_b64 s[78:79], s[10:11]
	v_add_f32_e32 v70, v70, v71
	ds_write_b32 v245, v70 offset:3584
	s_or_b64 exec, exec, s[78:79]
	v_pk_mul_f32 v[70:71], v[136:137], v[76:77]
	v_pk_mul_f32 v[72:73], v[138:139], v[72:73]
	v_pk_mul_f32 v[64:65], v[138:139], v[64:65]
	s_waitcnt lgkmcnt(3)
	v_pk_fma_f32 v[70:71], v[140:141], v[92:93], v[70:71] op_sel_hi:[1,0,1]
	v_pk_fma_f32 v[72:73], v[142:143], v[92:93], v[72:73] op_sel_hi:[1,0,1]
	v_pk_mul_f32 v[74:75], v[136:137], v[74:75]
	v_pk_fma_f32 v[64:65], v[142:143], v[92:93], v[64:65] op_sel:[0,1,0]
	v_add_f32_e32 v66, v66, v68
	v_add_f32_e32 v68, v67, v69
	v_pk_fma_f32 v[74:75], v[140:141], v[92:93], v[74:75] op_sel:[0,1,0]
	v_pk_fma_f32 v[70:71], v[128:129], v[66:67], v[70:71] op_sel_hi:[1,0,1] neg_lo:[1,0,0] neg_hi:[1,0,0]
	v_pk_fma_f32 v[66:67], v[130:131], v[66:67], v[72:73] op_sel_hi:[1,0,1] neg_lo:[1,0,0] neg_hi:[1,0,0]
	v_pk_fma_f32 v[64:65], v[130:131], v[68:69], v[64:65] op_sel_hi:[1,0,1] neg_lo:[1,0,0] neg_hi:[1,0,0]
	v_pk_fma_f32 v[72:73], v[128:129], v[68:69], v[74:75] op_sel_hi:[1,0,1] neg_lo:[1,0,0] neg_hi:[1,0,0]
	s_waitcnt lgkmcnt(1)
	v_pk_mul_f32 v[68:69], v[134:135], v[66:67]
	v_pk_mul_f32 v[74:75], v[134:135], v[64:65]
	v_pk_fma_f32 v[68:69], v[132:133], v[70:71], v[68:69]
	v_pk_fma_f32 v[74:75], v[132:133], v[72:73], v[74:75]
	v_add_f32_e32 v76, v68, v69
	v_add_f32_e32 v77, v74, v75
	v_pk_mul_f32 v[68:69], v[110:111], v[66:67]
	v_pk_mul_f32 v[74:75], v[110:111], v[64:65]
	v_pk_fma_f32 v[68:69], v[108:109], v[70:71], v[68:69]
	v_pk_fma_f32 v[74:75], v[108:109], v[72:73], v[74:75]
	v_add_f32_e32 v78, v68, v69
	v_add_f32_e32 v74, v74, v75
	v_pk_mul_f32 v[68:69], v[100:101], v[70:71]
	v_pk_mul_f32 v[70:71], v[100:101], v[72:73]
	v_add_f32_dpp v72, v78, v78 quad_perm:[1,0,3,2] row_mask:0xf bank_mask:0xf bound_ctrl:1
	v_add_f32_dpp v73, v74, v74 quad_perm:[1,0,3,2] row_mask:0xf bank_mask:0xf bound_ctrl:1
	v_pk_mul_f32 v[66:67], v[102:103], v[66:67]
	v_add_f32_dpp v72, v72, v72 quad_perm:[2,3,0,1] row_mask:0xf bank_mask:0xf bound_ctrl:1
	v_add_f32_dpp v73, v73, v73 quad_perm:[2,3,0,1] row_mask:0xf bank_mask:0xf bound_ctrl:1
	v_pk_mul_f32 v[64:65], v[102:103], v[64:65]
	v_add_f32_dpp v72, v72, v72 row_ror:4 row_mask:0xf bank_mask:0xf bound_ctrl:1
	v_add_f32_dpp v73, v73, v73 row_ror:4 row_mask:0xf bank_mask:0xf bound_ctrl:1
	v_pk_fma_f32 v[66:67], v[106:107], v[94:95], v[66:67] op_sel_hi:[1,0,1]
	v_pk_fma_f32 v[64:65], v[106:107], v[94:95], v[64:65] op_sel:[0,1,0]
	v_add_f32_dpp v72, v72, v72 row_ror:8 row_mask:0xf bank_mask:0xf bound_ctrl:1
	v_add_f32_dpp v74, v73, v73 row_ror:8 row_mask:0xf bank_mask:0xf bound_ctrl:1
	v_pk_fma_f32 v[68:69], v[104:105], v[94:95], v[68:69] op_sel_hi:[1,0,1]
	v_pk_fma_f32 v[70:71], v[104:105], v[94:95], v[70:71] op_sel:[0,1,0]
	v_pk_fma_f32 v[90:91], v[86:87], v[72:73], v[66:67] op_sel_hi:[1,0,1] neg_lo:[1,0,0] neg_hi:[1,0,0]
	v_pk_fma_f32 v[94:95], v[86:87], v[74:75], v[64:65] op_sel_hi:[1,0,1] neg_lo:[1,0,0] neg_hi:[1,0,0]
	v_pk_fma_f32 v[88:89], v[84:85], v[72:73], v[68:69] op_sel_hi:[1,0,1] neg_lo:[1,0,0] neg_hi:[1,0,0]
	v_pk_fma_f32 v[92:93], v[84:85], v[74:75], v[70:71] op_sel_hi:[1,0,1] neg_lo:[1,0,0] neg_hi:[1,0,0]
	s_waitcnt lgkmcnt(0)
	v_pk_mul_f32 v[64:65], v[98:99], v[90:91]
	v_pk_mul_f32 v[66:67], v[98:99], v[94:95]
	v_pk_fma_f32 v[64:65], v[96:97], v[88:89], v[64:65]
	v_pk_fma_f32 v[66:67], v[96:97], v[92:93], v[66:67]
	v_add_f32_e32 v64, v64, v65
	v_add_f32_e32 v65, v66, v67
	v_cndmask_b32_e64 v66, v76, v77, s[6:7]
	v_cndmask_b32_e64 v67, v64, v65, s[6:7]
	v_cndmask_b32_e64 v68, v77, v76, s[6:7]
	v_cndmask_b32_e64 v64, v65, v64, s[6:7]
	s_nop 0
	v_add_f32_dpp v65, v66, v68 quad_perm:[1,0,3,2] row_mask:0xf bank_mask:0xf bound_ctrl:1
	v_add_f32_dpp v64, v67, v64 quad_perm:[1,0,3,2] row_mask:0xf bank_mask:0xf bound_ctrl:1
	v_cndmask_b32_e64 v66, v65, v64, s[8:9]
	v_cndmask_b32_e64 v64, v64, v65, s[8:9]
	v_mov_b32_e32 v65, 0
	s_nop 0
	v_add_f32_dpp v64, v66, v64 quad_perm:[2,3,0,1] row_mask:0xf bank_mask:0xf bound_ctrl:1
	s_nop 1
	v_add_f32_dpp v64, v64, v64 row_ror:4 row_mask:0xf bank_mask:0xf bound_ctrl:1
	s_nop 1
	v_mov_b32_dpp v65, v64 row_ror:8 row_mask:0xf bank_mask:0xf
	s_and_saveexec_b64 s[78:79], s[10:11]
	v_add3_u32 v66, v176, v239, v197
	v_add_f32_e32 v64, v64, v65
	ds_write_b32 v66, v64 offset:3840
	s_or_b64 exec, exec, s[78:79]
	s_ashr_i32 s28, s24, 5
	s_add_i32 s29, s24, 0xffffff00
	s_not_b32 s28, s28
	s_lshr_b32 s29, s29, 5
	s_cmpk_lt_i32 s24, 0x100
	s_cselect_b32 s28, s28, s29
	s_ashr_i32 s29, s28, 31
	s_lshl_b32 s24, s24, 5
	s_lshl_b64 s[28:29], s[28:29], 10
	s_and_b32 s24, s24, 0x3e0
	s_or_b32 s24, s28, s24
	v_mov_b32_e32 v65, s29
	v_or_b32_e32 v64, s24, v192
	v_lshlrev_b64 v[64:65], 8, v[64:65]
	v_lshl_add_u64 v[64:65], v[198:199], 0, v[64:65]
	global_store_dwordx4 v[64:65], v[88:91], off
	global_store_dwordx4 v[64:65], v[92:95], off offset:256

.LBB0_360:
	s_waitcnt vmcnt(1)
	v_mov_b64_e32 v[42:43], v[22:23]
	s_waitcnt vmcnt(0)
	v_mov_b64_e32 v[46:47], v[18:19]
	s_sub_i32 s24, 0x810, s4
	s_and_b32 s47, s27, 1
	v_mov_b64_e32 v[40:41], v[20:21]
	v_mov_b64_e32 v[44:45], v[16:17]
	s_min_i32 s24, s24, 32
	v_lshl_add_u32 v132, s47, 12, v236
	s_cmpk_gt_i32 s4, 0x80f
	v_mov_b32_e32 v131, 0
	s_cbranch_scc1 .LBB0_371
	s_mul_i32 s47, s47, 0xb000
	s_add_i32 s28, s47, 0
	v_lshl_add_u32 v134, v192, 2, s28
	v_add_u32_e32 v72, 0xa000, v134
	v_add_u32_e32 v133, s28, v196
	ds_read2_b64 v[16:19], v72 offset1:16
	ds_read_b128 v[20:23], v133 offset:33024
	ds_read_b128 v[24:27], v133 offset:32768
	ds_read_b128 v[28:31], v133 offset:24832
	ds_read_b128 v[48:51], v133 offset:24576
	ds_read_b128 v[52:55], v133 offset:16640
	ds_read_b128 v[56:59], v133 offset:16384
	ds_read_b128 v[60:63], v133 offset:8448
	ds_read_b128 v[64:67], v133 offset:8192
	ds_read_b128 v[68:71], v133 offset:256
	ds_read_b128 v[112:115], v133
	ds_read2_b64 v[80:83], v72 offset0:32 offset1:48
	ds_read_b128 v[104:107], v133 offset:512
	ds_read_b128 v[84:87], v133 offset:768
	ds_read_b128 v[120:123], v133 offset:8704
	ds_read_b128 v[92:95], v133 offset:8960
	ds_read_b128 v[96:99], v133 offset:16896
	ds_read_b128 v[72:75], v133 offset:17152
	ds_read_b128 v[108:111], v133 offset:25088
	ds_read_b128 v[88:91], v133 offset:25344
	ds_read_b128 v[100:103], v133 offset:33280
	ds_read_b128 v[76:79], v133 offset:33536
	s_waitcnt lgkmcnt(13)
	v_pk_mul_f32 v[116:117], v[202:203], v[66:67]
	v_pk_mul_f32 v[66:67], v[206:207], v[66:67]
	v_pk_fma_f32 v[116:117], v[204:205], v[64:65], v[116:117]
	v_pk_fma_f32 v[64:65], v[208:209], v[64:65], v[66:67]
	v_add_f32_e32 v66, v116, v117
	v_add_f32_e32 v64, v64, v65
	s_waitcnt lgkmcnt(11)
	v_pk_mul_f32 v[116:117], v[206:207], v[114:115]
	v_add_f32_dpp v65, v66, v66 quad_perm:[1,0,3,2] row_mask:0xf bank_mask:0xf bound_ctrl:1
	v_add_f32_dpp v64, v64, v64 quad_perm:[1,0,3,2] row_mask:0xf bank_mask:0xf bound_ctrl:1
	v_pk_fma_f32 v[116:117], v[16:17], v[50:51], v[116:117] op_sel:[1,0,0]
	v_add_f32_dpp v65, v65, v65 quad_perm:[2,3,0,1] row_mask:0xf bank_mask:0xf bound_ctrl:1
	v_add_f32_dpp v64, v64, v64 quad_perm:[2,3,0,1] row_mask:0xf bank_mask:0xf bound_ctrl:1
	s_nop 0
	v_add_f32_dpp v118, v65, v65 row_ror:4 row_mask:0xf bank_mask:0xf bound_ctrl:1
	v_add_f32_dpp v66, v64, v64 row_ror:4 row_mask:0xf bank_mask:0xf bound_ctrl:1
	v_pk_mul_f32 v[64:65], v[208:209], v[112:113]
	v_pk_mul_f32 v[112:113], v[204:205], v[112:113]
	v_pk_fma_f32 v[64:65], v[16:17], v[48:49], v[64:65] op_sel:[1,0,0]
	v_add_f32_dpp v66, v66, v66 row_ror:8 row_mask:0xf bank_mask:0xf bound_ctrl:1
	v_pk_fma_f32 v[48:49], v[16:17], v[48:49], v[112:113] op_sel_hi:[0,1,1]
	v_add_f32_dpp v112, v118, v118 row_ror:8 row_mask:0xf bank_mask:0xf bound_ctrl:1
	v_pk_fma_f32 v[64:65], v[56:57], v[66:67], v[64:65] op_sel_hi:[1,0,1] neg_lo:[1,0,0] neg_hi:[1,0,0]
	v_pk_fma_f32 v[48:49], v[56:57], v[112:113], v[48:49] op_sel_hi:[1,0,1] neg_lo:[1,0,0] neg_hi:[1,0,0]
	v_pk_mul_f32 v[56:57], v[202:203], v[114:115]
	v_pk_fma_f32 v[66:67], v[58:59], v[66:67], v[116:117] op_sel_hi:[1,0,1] neg_lo:[1,0,0] neg_hi:[1,0,0]
	v_pk_fma_f32 v[16:17], v[16:17], v[50:51], v[56:57] op_sel_hi:[0,1,1]
	v_pk_fma_f32 v[16:17], v[58:59], v[112:113], v[16:17] op_sel_hi:[1,0,1] neg_lo:[1,0,0] neg_hi:[1,0,0]
	v_pk_mul_f32 v[116:117], v[26:27], v[66:67]
	v_pk_mul_f32 v[26:27], v[26:27], v[16:17]
	v_pk_fma_f32 v[116:117], v[24:25], v[64:65], v[116:117]
	v_pk_fma_f32 v[24:25], v[24:25], v[48:49], v[26:27]
	v_pk_mul_f32 v[26:27], v[62:63], v[66:67]
	v_add_f32_e32 v131, v24, v25
	v_pk_mul_f32 v[24:25], v[62:63], v[16:17]
	v_pk_fma_f32 v[26:27], v[60:61], v[64:65], v[26:27]
	v_pk_fma_f32 v[24:25], v[60:61], v[48:49], v[24:25]
	v_add_f32_e32 v51, v26, v27
	v_add_f32_e32 v50, v24, v25
	v_pk_mul_f32 v[24:25], v[68:69], v[48:49]
	v_pk_mul_f32 v[26:27], v[68:69], v[64:65]
	v_pk_fma_f32 v[24:25], v[18:19], v[28:29], v[24:25] op_sel_hi:[0,1,1]
	v_pk_mul_f32 v[16:17], v[70:71], v[16:17]
	v_pk_fma_f32 v[26:27], v[18:19], v[28:29], v[26:27] op_sel:[1,0,0]
	v_pk_mul_f32 v[28:29], v[70:71], v[66:67]
	v_pk_fma_f32 v[16:17], v[18:19], v[30:31], v[16:17] op_sel_hi:[0,1,1]
	v_pk_fma_f32 v[18:19], v[18:19], v[30:31], v[28:29] op_sel:[1,0,0]
	v_add_f32_dpp v28, v50, v50 quad_perm:[1,0,3,2] row_mask:0xf bank_mask:0xf bound_ctrl:1
	v_add_f32_dpp v29, v51, v51 quad_perm:[1,0,3,2] row_mask:0xf bank_mask:0xf bound_ctrl:1
	v_add_f32_e32 v130, v116, v117
	v_add_f32_dpp v28, v28, v28 quad_perm:[2,3,0,1] row_mask:0xf bank_mask:0xf bound_ctrl:1
	v_add_f32_dpp v29, v29, v29 quad_perm:[2,3,0,1] row_mask:0xf bank_mask:0xf bound_ctrl:1
	s_nop 0
	v_add_f32_dpp v28, v28, v28 row_ror:4 row_mask:0xf bank_mask:0xf bound_ctrl:1
	v_add_f32_dpp v29, v29, v29 row_ror:4 row_mask:0xf bank_mask:0xf bound_ctrl:1
	s_nop 0
	v_add_f32_dpp v28, v28, v28 row_ror:8 row_mask:0xf bank_mask:0xf bound_ctrl:1
	v_add_f32_dpp v30, v29, v29 row_ror:8 row_mask:0xf bank_mask:0xf bound_ctrl:1
	v_pk_fma_f32 v[114:115], v[54:55], v[28:29], v[16:17] op_sel_hi:[1,0,1] neg_lo:[1,0,0] neg_hi:[1,0,0]
	v_pk_fma_f32 v[112:113], v[54:55], v[30:31], v[18:19] op_sel_hi:[1,0,1] neg_lo:[1,0,0] neg_hi:[1,0,0]
	v_pk_fma_f32 v[118:119], v[52:53], v[28:29], v[24:25] op_sel_hi:[1,0,1] neg_lo:[1,0,0] neg_hi:[1,0,0]
	v_pk_fma_f32 v[116:117], v[52:53], v[30:31], v[26:27] op_sel_hi:[1,0,1] neg_lo:[1,0,0] neg_hi:[1,0,0]
	v_pk_mul_f32 v[16:17], v[22:23], v[114:115]
	v_pk_mul_f32 v[18:19], v[22:23], v[112:113]
	v_pk_fma_f32 v[16:17], v[20:21], v[118:119], v[16:17]
	v_pk_fma_f32 v[18:19], v[20:21], v[116:117], v[18:19]
	v_add_f32_e32 v135, v16, v17
	v_add_f32_e32 v136, v18, v19
	s_cmpk_lt_i32 s4, 0x80c
	s_cselect_b64 s[78:79], -1, 0
	s_and_b64 s[28:29], s[78:79], exec
	s_cselect_b32 s28, 4, 0
	v_lshl_add_u32 v16, s28, 8, v133
	v_lshl_add_u32 v17, s28, 7, v134
	s_or_b32 s28, s28, 1
	v_lshl_add_u32 v56, s28, 8, v133
	ds_read_b128 v[68:71], v16 offset:8192
	ds_read_b128 v[28:31], v16 offset:16384
	ds_read_b128 v[60:63], v16
	ds_read_b128 v[52:55], v16 offset:32768
	ds_read_b128 v[64:67], v16 offset:24576
	ds_read_b64 v[126:127], v17 offset:40960
	ds_read_b128 v[48:51], v56 offset:8192
	ds_read_b128 v[16:19], v56 offset:16384
	ds_read_b128 v[24:27], v56
	ds_read_b128 v[20:23], v56 offset:32768
	v_lshl_add_u32 v124, s28, 7, v134
	ds_read_b128 v[56:59], v56 offset:24576
	ds_read_b64 v[124:125], v124 offset:40960
	s_waitcnt lgkmcnt(14)
	v_pk_mul_f32 v[128:129], v[122:123], v[114:115]
	v_pk_mul_f32 v[122:123], v[122:123], v[112:113]
	v_pk_fma_f32 v[128:129], v[120:121], v[118:119], v[128:129]
	v_pk_fma_f32 v[120:121], v[120:121], v[116:117], v[122:123]
	v_add_f32_e32 v122, v128, v129
	v_cndmask_b32_e64 v128, v131, v130, s[6:7]
	v_cndmask_b32_e64 v129, v135, v136, s[6:7]
	v_cndmask_b32_e64 v130, v130, v131, s[6:7]
	v_cndmask_b32_e64 v131, v136, v135, s[6:7]
	v_add_f32_e32 v120, v120, v121
	v_add_f32_dpp v128, v128, v130 quad_perm:[1,0,3,2] row_mask:0xf bank_mask:0xf bound_ctrl:1
	v_add_f32_dpp v129, v129, v131 quad_perm:[1,0,3,2] row_mask:0xf bank_mask:0xf bound_ctrl:1
	v_add_f32_dpp v121, v122, v122 quad_perm:[1,0,3,2] row_mask:0xf bank_mask:0xf bound_ctrl:1
	v_add_f32_dpp v120, v120, v120 quad_perm:[1,0,3,2] row_mask:0xf bank_mask:0xf bound_ctrl:1
	v_cndmask_b32_e64 v130, v128, v129, s[8:9]
	v_cndmask_b32_e64 v128, v129, v128, s[8:9]
	v_add_f32_dpp v121, v121, v121 quad_perm:[2,3,0,1] row_mask:0xf bank_mask:0xf bound_ctrl:1
	v_add_f32_dpp v122, v120, v120 quad_perm:[2,3,0,1] row_mask:0xf bank_mask:0xf bound_ctrl:1
	v_add_f32_dpp v128, v130, v128 quad_perm:[2,3,0,1] row_mask:0xf bank_mask:0xf bound_ctrl:1
	v_add_f32_dpp v120, v121, v121 row_ror:4 row_mask:0xf bank_mask:0xf bound_ctrl:1
	v_add_f32_dpp v121, v122, v122 row_ror:4 row_mask:0xf bank_mask:0xf bound_ctrl:1
	v_mov_b32_e32 v122, v177
	v_mov_b32_e32 v123, v177
	v_add_f32_dpp v128, v128, v128 row_ror:4 row_mask:0xf bank_mask:0xf bound_ctrl:1
	v_mov_b32_e32 v129, v177
	v_mov_b32_dpp v122, v120 row_ror:8 row_mask:0xf bank_mask:0xf
	v_mov_b32_dpp v123, v121 row_ror:8 row_mask:0xf bank_mask:0xf
	v_mov_b32_dpp v129, v128 row_ror:8 row_mask:0xf bank_mask:0xf
	s_and_saveexec_b64 s[80:81], s[10:11]
	v_add3_u32 v130, v132, v197, v240
	v_add_f32_e32 v128, v128, v129
	ds_write_b32 v130, v128
	s_or_b64 exec, exec, s[80:81]
	v_pk_mul_f32 v[118:119], v[104:105], v[118:119]
	v_pk_mul_f32 v[114:115], v[106:107], v[114:115]
	v_pk_mul_f32 v[104:105], v[104:105], v[116:117]
	v_pk_mul_f32 v[106:107], v[106:107], v[112:113]
	v_pk_fma_f32 v[118:119], v[108:109], v[80:81], v[118:119] op_sel_hi:[1,0,1]
	v_pk_fma_f32 v[114:115], v[110:111], v[80:81], v[114:115] op_sel_hi:[1,0,1]
	v_pk_fma_f32 v[104:105], v[108:109], v[80:81], v[104:105] op_sel:[0,1,0]
	v_pk_fma_f32 v[80:81], v[110:111], v[80:81], v[106:107] op_sel:[0,1,0]
	v_add_f32_e32 v106, v120, v122
	v_add_f32_e32 v108, v121, v123
	v_pk_fma_f32 v[110:111], v[96:97], v[106:107], v[118:119] op_sel_hi:[1,0,1] neg_lo:[1,0,0] neg_hi:[1,0,0]
	v_pk_fma_f32 v[106:107], v[98:99], v[106:107], v[114:115] op_sel_hi:[1,0,1] neg_lo:[1,0,0] neg_hi:[1,0,0]
	v_pk_fma_f32 v[80:81], v[98:99], v[108:109], v[80:81] op_sel_hi:[1,0,1] neg_lo:[1,0,0] neg_hi:[1,0,0]
	v_pk_fma_f32 v[96:97], v[96:97], v[108:109], v[104:105] op_sel_hi:[1,0,1] neg_lo:[1,0,0] neg_hi:[1,0,0]
	s_waitcnt lgkmcnt(13)
	v_pk_mul_f32 v[98:99], v[102:103], v[106:107]
	v_pk_mul_f32 v[102:103], v[102:103], v[80:81]
	v_pk_fma_f32 v[98:99], v[100:101], v[110:111], v[98:99]
	v_pk_fma_f32 v[100:101], v[100:101], v[96:97], v[102:103]
	v_mov_b32_e32 v103, v98
	v_mov_b32_e32 v102, v100
	v_mov_b32_e32 v98, v101
	v_pk_add_f32 v[128:129], v[102:103], v[98:99]
	v_pk_mul_f32 v[98:99], v[94:95], v[106:107]
	v_pk_mul_f32 v[94:95], v[94:95], v[80:81]
	v_pk_fma_f32 v[98:99], v[92:93], v[110:111], v[98:99]
	v_pk_fma_f32 v[92:93], v[92:93], v[96:97], v[94:95]
	v_add_f32_e32 v98, v98, v99
	v_add_f32_e32 v99, v92, v93
	v_pk_mul_f32 v[92:93], v[84:85], v[110:111]
	v_pk_mul_f32 v[94:95], v[86:87], v[106:107]
	v_pk_mul_f32 v[84:85], v[84:85], v[96:97]
	v_pk_mul_f32 v[80:81], v[86:87], v[80:81]
	v_pk_fma_f32 v[92:93], v[88:89], v[82:83], v[92:93] op_sel_hi:[1,0,1]
	v_pk_fma_f32 v[94:95], v[90:91], v[82:83], v[94:95] op_sel_hi:[1,0,1]
	v_pk_fma_f32 v[84:85], v[88:89], v[82:83], v[84:85] op_sel:[0,1,0]
	v_pk_fma_f32 v[80:81], v[90:91], v[82:83], v[80:81] op_sel:[0,1,0]
	v_add_f32_dpp v82, v98, v98 quad_perm:[1,0,3,2] row_mask:0xf bank_mask:0xf bound_ctrl:1
	v_add_f32_dpp v83, v99, v99 quad_perm:[1,0,3,2] row_mask:0xf bank_mask:0xf bound_ctrl:1
	s_nop 0
	v_add_f32_dpp v82, v82, v82 quad_perm:[2,3,0,1] row_mask:0xf bank_mask:0xf bound_ctrl:1
	v_add_f32_dpp v83, v83, v83 quad_perm:[2,3,0,1] row_mask:0xf bank_mask:0xf bound_ctrl:1
	s_nop 0
	v_add_f32_dpp v82, v82, v82 row_ror:4 row_mask:0xf bank_mask:0xf bound_ctrl:1
	v_add_f32_dpp v83, v83, v83 row_ror:4 row_mask:0xf bank_mask:0xf bound_ctrl:1
	s_nop 0
	v_add_f32_dpp v82, v82, v82 row_ror:8 row_mask:0xf bank_mask:0xf bound_ctrl:1
	v_add_f32_dpp v86, v83, v83 row_ror:8 row_mask:0xf bank_mask:0xf bound_ctrl:1
	v_pk_fma_f32 v[90:91], v[74:75], v[82:83], v[94:95] op_sel_hi:[1,0,1] neg_lo:[1,0,0] neg_hi:[1,0,0]
	v_pk_fma_f32 v[94:95], v[74:75], v[86:87], v[80:81] op_sel_hi:[1,0,1] neg_lo:[1,0,0] neg_hi:[1,0,0]
	v_pk_fma_f32 v[88:89], v[72:73], v[82:83], v[92:93] op_sel_hi:[1,0,1] neg_lo:[1,0,0] neg_hi:[1,0,0]
	v_pk_fma_f32 v[92:93], v[72:73], v[86:87], v[84:85] op_sel_hi:[1,0,1] neg_lo:[1,0,0] neg_hi:[1,0,0]
	s_waitcnt lgkmcnt(12)
	v_pk_mul_f32 v[72:73], v[78:79], v[90:91]
	v_pk_mul_f32 v[74:75], v[78:79], v[94:95]
	v_pk_fma_f32 v[72:73], v[76:77], v[88:89], v[72:73]
	v_pk_fma_f32 v[74:75], v[76:77], v[92:93], v[74:75]
	v_mov_b32_e32 v77, v72
	v_mov_b32_e32 v76, v74
	v_mov_b32_e32 v72, v75
	v_pk_add_f32 v[130:131], v[76:77], v[72:73]
	s_andn2_b64 vcc, exec, s[78:79]
	s_cbranch_vccnz .LBB0_372
	v_cndmask_b32_e64 v72, 0, 1, s[72:73]
	s_mov_b32 s28, 0xb000
	v_lshl_or_b32 v135, v72, 12, v241
	v_mul_lo_u32 v72, v72, s28
	v_add_u32_e32 v136, v242, v72
	v_or_b32_e32 v137, v243, v72
	s_mov_b32 s47, 4

.LBB0_372:
	s_waitcnt lgkmcnt(4)
	v_cndmask_b32_e64 v16, v129, v128, s[6:7]
	v_cndmask_b32_e64 v17, v131, v130, s[6:7]
	v_cndmask_b32_e64 v18, v128, v129, s[6:7]
	v_cndmask_b32_e64 v19, v130, v131, s[6:7]
	s_nop 0
	v_add_f32_dpp v16, v16, v18 quad_perm:[1,0,3,2] row_mask:0xf bank_mask:0xf bound_ctrl:1
	v_add_f32_dpp v17, v17, v19 quad_perm:[1,0,3,2] row_mask:0xf bank_mask:0xf bound_ctrl:1
	v_cndmask_b32_e64 v18, v16, v17, s[8:9]
	v_cndmask_b32_e64 v16, v17, v16, s[8:9]
	v_mov_b32_e32 v17, v177
	s_nop 0
	v_add_f32_dpp v16, v18, v16 quad_perm:[2,3,0,1] row_mask:0xf bank_mask:0xf bound_ctrl:1
	s_nop 1
	v_add_f32_dpp v16, v16, v16 row_ror:4 row_mask:0xf bank_mask:0xf bound_ctrl:1
	s_nop 1
	v_mov_b32_dpp v17, v16 row_ror:8 row_mask:0xf bank_mask:0xf
	s_and_saveexec_b64 s[78:79], s[10:11]
	v_add_lshl_u32 v18, s24, v238, 7
	v_add3_u32 v18, v132, v18, v197
	v_add_f32_e32 v16, v16, v17
	ds_write_b32 v18, v16
	s_or_b64 exec, exec, s[78:79]
	s_andn2_b64 vcc, exec, s[76:77]
	s_cbranch_vccnz .LBB0_376
	s_ashr_i32 s28, s70, 5
	s_ashr_i32 s29, s28, 31
	s_lshl_b32 s24, s70, 5
	s_lshl_b64 s[28:29], s[28:29], 10
	s_and_b32 s47, s24, 0x3c0
	s_or_b32 s28, s28, s47
	s_and_b32 s24, s24, 32
	s_or_b32 s24, s28, s24
	v_mov_b32_e32 v17, s29
	v_or_b32_e32 v16, s24, v192
	v_lshlrev_b64 v[16:17], 8, v[16:17]
	v_lshl_add_u64 v[16:17], v[200:201], 0, v[16:17]
	global_store_dwordx4 v[16:17], v[88:91], off
	global_store_dwordx4 v[16:17], v[92:95], off offset:256
